# GEMM K-loops: address/m0 bookkeeping moved out of the MFMA segments into the adjacent load segments (across s_barrier, no LDS/DMA op moved)
# baseline (speedup 1.0000x reference)
; #define PG8_STAGE(bufoff, gbase, v0, v1) do { \
;         __builtin_amdgcn_global_load_lds((const unsigned*)((const char*)(gbase) + (v0)), (LAS unsigned*)(lds + (bufoff) + ldsw), 16, 0, 0); \
;         __builtin_amdgcn_global_load_lds((const unsigned*)((const char*)(gbase) + (v1)), (LAS unsigned*)(lds + (bufoff) + ldsw + 8192), 16, 0, 0); } while (0)
; #define PG8_LDA(dst, b, h) do { _Pragma("unroll") for (int m = 0; m < 4; ++m) _Pragma("unroll") for (int k = 0; k < 2; ++k) dst[m][k] = *(const LAS bf16x8*)(lds + PG8_SA(b, h) + aoff + m * 2048 + k * 1024); } while (0)
; #define PG8_LDB(dst, b, h) do { _Pragma("unroll") for (int n = 0; n < 2; ++n) _Pragma("unroll") for (int k = 0; k < 2; ++k) dst[n][k] = *(const LAS bf16x8*)(lds + PG8_SB(b, h) + boff + n * 2048 + k * 1024); } while (0)
; #define PG8_MMA(ai, bj, At, Bt) do { __builtin_amdgcn_s_setprio(1); _Pragma("unroll") for (int m = 0; m < 4; ++m) _Pragma("unroll") for (int n = 0; n < 2; ++n) _Pragma("unroll") for (int k = 0; k < 2; ++k) \
;         acc[ai][bj][m][n] = __builtin_amdgcn_mfma_f32_16x16x32_bf16(Bt[n][k], At[m][k], acc[ai][bj][m][n], 0, 0, 0); __builtin_amdgcn_s_setprio(0); } while (0)
; #define PG8_WAIT_L(n) asm volatile("s_waitcnt lgkmcnt(" #n ")" ::: "memory")
; #define PG8_BAR __builtin_amdgcn_s_barrier()
; template <class Epi, class Sched>
; __device__ __forceinline__ void gemm_phase(LAS unsigned char* lds, const Sched& S, const Epi& E) {
;     ...
;             const char* a1 = cA + (size_t)(t + 1) * kstep;
;             const char* a2 = last ? nA : cA + (size_t)(t + 2) * kstep; const char* b2 = last ? nB : cB + (size_t)(t + 2) * kstep;
;             const char* a3 = a2 + kstep; const char* b3 = b2 + kstep;
;             const unsigned xA0 = last ? nvA0 : vA0, xA1 = last ? nvA1 : vA1, xB0 = last ? nvB0 : vB0, xB1 = last ? nvB1 : vB1;
;             const size_t xhA = last ? nhA : hA, xhB = last ? nhB : hB;
;             PG8_LDB(B0, 0, 0); PG8_SCHED; PG8_LDA(At, 0, 0); PG8_STAGE(PG8_SA(1, 1), a1 + hA, vA0, vA1);
;             PG8_WAIT_L(8); PG8_BAR; PG8_WAIT_L(0); PG8_MMA(0, 0, At, B0); PG8_BAR; PG8_SCHED;
;             PG8_LDB(B1, 0, 1); PG8_STAGE(PG8_SB(0, 0), b2, xB0, xB1);
;             PG8_BAR; PG8_WAIT_L(0); PG8_MMA(0, 1, At, B1); PG8_BAR;
;             PG8_LDA(At, 0, 1); PG8_STAGE(PG8_SA(0, 0), a2, xA0, xA1);
;             PG8_BAR; PG8_WAIT_L(0); PG8_MMA(1, 0, At, B0); PG8_BAR; PG8_SCHED;
.LBB0_306:
	s_add_u32 s21, s26, 0xfff80080
	s_addc_u32 s69, s27, -1
	s_and_b64 s[40:41], exec, s[40:41]
	s_cselect_b32 s41, s23, s69
	s_cselect_b32 s40, s22, s21
	s_add_i32 s21, 0, 0x10000
	v_add_u32_e32 v138, s21, v153
	ds_read_b128 v[158:161], v138
	ds_read_b128 v[182:185], v138 offset:1024
	ds_read_b128 v[186:189], v138 offset:2048
	ds_read_b128 v[190:193], v138 offset:3072
	v_lshl_add_u64 v[226:227], s[26:27], 0, v[132:133]
	s_add_i32 m0, s48, 0xc000
	ds_read_b128 v[194:197], v154
	ds_read_b128 v[198:201], v154 offset:1024
	ds_read_b128 v[202:205], v154 offset:2048
	ds_read_b128 v[206:209], v154 offset:3072
	ds_read_b128 v[210:213], v154 offset:4096
	ds_read_b128 v[214:217], v154 offset:5120
	ds_read_b128 v[218:221], v154 offset:6144
	ds_read_b128 v[222:225], v154 offset:7168
	global_load_lds_dwordx4 v[226:227], off
	v_lshl_add_u64 v[226:227], s[26:27], 0, v[134:135]
	s_add_i32 m0, s48, 0xe000
	s_nop 0
	global_load_lds_dwordx4 v[226:227], off
	s_waitcnt lgkmcnt(8)
	s_barrier
	s_waitcnt lgkmcnt(0)
	s_setprio 1
	v_mfma_f32_16x16x32_bf16 v[124:127], v[158:161], v[194:197], v[124:127]
	v_mfma_f32_16x16x32_bf16 v[120:123], v[186:189], v[194:197], v[120:123]
	v_mfma_f32_16x16x32_bf16 v[116:119], v[158:161], v[202:205], v[116:119]
	v_mfma_f32_16x16x32_bf16 v[112:115], v[186:189], v[202:205], v[112:115]
	v_mfma_f32_16x16x32_bf16 v[100:103], v[158:161], v[210:213], v[100:103]
	v_mfma_f32_16x16x32_bf16 v[96:99], v[186:189], v[210:213], v[96:99]
	v_mfma_f32_16x16x32_bf16 v[84:87], v[158:161], v[218:221], v[84:87]
	v_mfma_f32_16x16x32_bf16 v[80:83], v[186:189], v[218:221], v[80:83]
	v_mfma_f32_16x16x32_bf16 v[124:127], v[182:185], v[198:201], v[124:127]
	v_mfma_f32_16x16x32_bf16 v[120:123], v[190:193], v[198:201], v[120:123]
	v_mfma_f32_16x16x32_bf16 v[116:119], v[182:185], v[206:209], v[116:119]
	v_mfma_f32_16x16x32_bf16 v[112:115], v[190:193], v[206:209], v[112:115]
	v_mfma_f32_16x16x32_bf16 v[100:103], v[182:185], v[214:217], v[100:103]
	v_mfma_f32_16x16x32_bf16 v[96:99], v[190:193], v[214:217], v[96:99]
	v_mfma_f32_16x16x32_bf16 v[84:87], v[182:185], v[222:225], v[84:87]
	v_mfma_f32_16x16x32_bf16 v[80:83], v[190:193], v[222:225], v[80:83]
	s_setprio 0
	s_barrier
	s_add_i32 s69, 0, 0x14000
	s_add_i32 s21, s21, s43
	v_add_u32_e32 v138, s69, v153
	s_mov_b32 m0, s21
	ds_read_b128 v[226:229], v138
	ds_read_b128 v[230:233], v138 offset:1024
	ds_read_b128 v[234:237], v138 offset:2048
	ds_read_b128 v[238:241], v138 offset:3072
	global_load_lds_dwordx4 v136, s[38:39]
	s_add_i32 m0, s21, 0x2000
	v_mov_b32_e32 v147, v137
	global_load_lds_dwordx4 v146, s[38:39]
	v_lshl_add_u64 v[242:243], s[38:39], 0, v[136:137]
	v_lshl_add_u64 v[244:245], s[38:39], 0, v[146:147]
	s_barrier
	s_waitcnt lgkmcnt(0)
	s_setprio 1
	v_mfma_f32_16x16x32_bf16 v[108:111], v[226:229], v[194:197], v[108:111]
	v_mfma_f32_16x16x32_bf16 v[104:107], v[234:237], v[194:197], v[104:107]
	v_mfma_f32_16x16x32_bf16 v[92:95], v[226:229], v[202:205], v[92:95]
	v_mfma_f32_16x16x32_bf16 v[88:91], v[234:237], v[202:205], v[88:91]
	v_mfma_f32_16x16x32_bf16 v[76:79], v[226:229], v[210:213], v[76:79]
	v_mfma_f32_16x16x32_bf16 v[72:75], v[234:237], v[210:213], v[72:75]
	v_mfma_f32_16x16x32_bf16 v[68:71], v[226:229], v[218:221], v[68:71]
	v_mfma_f32_16x16x32_bf16 v[64:67], v[234:237], v[218:221], v[64:67]
	v_mfma_f32_16x16x32_bf16 v[108:111], v[230:233], v[198:201], v[108:111]
	v_mfma_f32_16x16x32_bf16 v[104:107], v[238:241], v[198:201], v[104:107]
	v_mfma_f32_16x16x32_bf16 v[92:95], v[230:233], v[206:209], v[92:95]
	v_mfma_f32_16x16x32_bf16 v[88:91], v[238:241], v[206:209], v[88:91]
	v_mfma_f32_16x16x32_bf16 v[76:79], v[230:233], v[214:217], v[76:79]
	v_mfma_f32_16x16x32_bf16 v[72:75], v[238:241], v[214:217], v[72:75]
	v_mfma_f32_16x16x32_bf16 v[68:71], v[230:233], v[222:225], v[68:71]
	v_mfma_f32_16x16x32_bf16 v[64:67], v[238:241], v[222:225], v[64:67]
	s_setprio 0
	s_barrier
	s_mov_b32 m0, s48
	v_lshl_add_u64 v[246:247], s[40:41], 0, v[150:151]
	ds_read_b128 v[194:197], v154 offset:16384
	ds_read_b128 v[198:201], v154 offset:17408
	ds_read_b128 v[202:205], v154 offset:18432
	ds_read_b128 v[206:209], v154 offset:19456
	ds_read_b128 v[210:213], v154 offset:20480
	ds_read_b128 v[214:217], v154 offset:21504
	ds_read_b128 v[218:221], v154 offset:22528
	ds_read_b128 v[222:225], v154 offset:23552
	global_load_lds_dwordx4 v[246:247], off
	v_lshl_add_u64 v[248:249], s[40:41], 0, v[148:149]
	s_mov_b32 m0, s49
	s_nop 0
	global_load_lds_dwordx4 v[248:249], off
	s_barrier
	s_waitcnt lgkmcnt(0)
	s_setprio 1
	v_mfma_f32_16x16x32_bf16 v[60:63], v[158:161], v[194:197], v[60:63]
	v_mfma_f32_16x16x32_bf16 v[56:59], v[186:189], v[194:197], v[56:59]
	v_mfma_f32_16x16x32_bf16 v[52:55], v[158:161], v[202:205], v[52:55]
	v_mfma_f32_16x16x32_bf16 v[44:47], v[186:189], v[202:205], v[44:47]
	v_mfma_f32_16x16x32_bf16 v[36:39], v[158:161], v[210:213], v[36:39]
	v_mfma_f32_16x16x32_bf16 v[28:31], v[186:189], v[210:213], v[28:31]
	v_mfma_f32_16x16x32_bf16 v[20:23], v[158:161], v[218:221], v[20:23]
	v_mfma_f32_16x16x32_bf16 v[12:15], v[186:189], v[218:221], v[12:15]
	v_mfma_f32_16x16x32_bf16 v[60:63], v[182:185], v[198:201], v[60:63]
	v_mfma_f32_16x16x32_bf16 v[56:59], v[190:193], v[198:201], v[56:59]
	v_mfma_f32_16x16x32_bf16 v[52:55], v[182:185], v[206:209], v[52:55]
	v_mfma_f32_16x16x32_bf16 v[44:47], v[190:193], v[206:209], v[44:47]
	v_mfma_f32_16x16x32_bf16 v[36:39], v[182:185], v[214:217], v[36:39]
	v_mfma_f32_16x16x32_bf16 v[28:31], v[190:193], v[214:217], v[28:31]
	v_mfma_f32_16x16x32_bf16 v[20:23], v[182:185], v[222:225], v[20:23]
	v_mfma_f32_16x16x32_bf16 v[12:15], v[190:193], v[222:225], v[12:15]
	s_setprio 0
	s_barrier
; #define PG8_STAGE(bufoff, gbase, v0, v1) do { \
;         __builtin_amdgcn_global_load_lds((const unsigned*)((const char*)(gbase) + (v0)), (LAS unsigned*)(lds + (bufoff) + ldsw), 16, 0, 0); \
;         __builtin_amdgcn_global_load_lds((const unsigned*)((const char*)(gbase) + (v1)), (LAS unsigned*)(lds + (bufoff) + ldsw + 8192), 16, 0, 0); } while (0)
; #define PG8_LDA(dst, b, h) do { _Pragma("unroll") for (int m = 0; m < 4; ++m) _Pragma("unroll") for (int k = 0; k < 2; ++k) dst[m][k] = *(const LAS bf16x8*)(lds + PG8_SA(b, h) + aoff + m * 2048 + k * 1024); } while (0)
; #define PG8_LDB(dst, b, h) do { _Pragma("unroll") for (int n = 0; n < 2; ++n) _Pragma("unroll") for (int k = 0; k < 2; ++k) dst[n][k] = *(const LAS bf16x8*)(lds + PG8_SB(b, h) + boff + n * 2048 + k * 1024); } while (0)
; #define PG8_MMA(ai, bj, At, Bt) do { __builtin_amdgcn_s_setprio(1); _Pragma("unroll") for (int m = 0; m < 4; ++m) _Pragma("unroll") for (int n = 0; n < 2; ++n) _Pragma("unroll") for (int k = 0; k < 2; ++k) \
;         acc[ai][bj][m][n] = __builtin_amdgcn_mfma_f32_16x16x32_bf16(Bt[n][k], At[m][k], acc[ai][bj][m][n], 0, 0, 0); __builtin_amdgcn_s_setprio(0); } while (0)
; #define PG8_WAIT_V(n) asm volatile("s_waitcnt vmcnt(" #n ")" ::: "memory")
; #define PG8_WAIT_L(n) asm volatile("s_waitcnt lgkmcnt(" #n ")" ::: "memory")
; #define PG8_BAR __builtin_amdgcn_s_barrier()
; #define PG8_SCHED __builtin_amdgcn_sched_barrier(0)
; template <class Epi, class Sched>
; __device__ __forceinline__ void gemm_phase(LAS unsigned char* lds, const Sched& S, const Epi& E) {
;     ...
;             PG8_STAGE(PG8_SB(0, 1), b2 + xhB, xB0, xB1);
;             PG8_WAIT_V(6); PG8_BAR; PG8_MMA(1, 1, At, B1); PG8_BAR;
;             PG8_LDB(B0, 1, 0); PG8_SCHED; PG8_LDA(At, 1, 0); PG8_STAGE(PG8_SA(0, 1), a2 + xhA, xA0, xA1);
;             PG8_WAIT_L(8); PG8_BAR; PG8_WAIT_L(0); PG8_MMA(0, 0, At, B0); PG8_BAR; PG8_SCHED;
;             PG8_LDB(B1, 1, 1); PG8_STAGE(PG8_SB(1, 0), b3, xB0, xB1);
	s_add_u32 s70, s38, 0x80000
	s_addc_u32 s71, s39, 0
	s_add_i32 s21, s69, s43
	s_mov_b32 m0, s21
	s_nop 0
	global_load_lds_dwordx4 v136, s[70:71]
	s_add_i32 m0, s21, 0x2000
	s_nop 0
	global_load_lds_dwordx4 v146, s[70:71]
	s_waitcnt vmcnt(6)
	s_barrier
	s_setprio 1
	v_mfma_f32_16x16x32_bf16 v[48:51], v[226:229], v[194:197], v[48:51]
	v_mfma_f32_16x16x32_bf16 v[40:43], v[234:237], v[194:197], v[40:43]
	v_mfma_f32_16x16x32_bf16 v[32:35], v[226:229], v[202:205], v[32:35]
	v_mfma_f32_16x16x32_bf16 v[24:27], v[234:237], v[202:205], v[24:27]
	v_mfma_f32_16x16x32_bf16 v[16:19], v[226:229], v[210:213], v[16:19]
	v_mfma_f32_16x16x32_bf16 v[8:11], v[234:237], v[210:213], v[8:11]
	v_mfma_f32_16x16x32_bf16 v[4:7], v[226:229], v[218:221], v[4:7]
	v_mfma_f32_16x16x32_bf16 v[0:3], v[234:237], v[218:221], v[0:3]
	v_mfma_f32_16x16x32_bf16 v[48:51], v[230:233], v[198:201], v[48:51]
	v_mfma_f32_16x16x32_bf16 v[40:43], v[238:241], v[198:201], v[40:43]
	v_mfma_f32_16x16x32_bf16 v[32:35], v[230:233], v[206:209], v[32:35]
	v_mfma_f32_16x16x32_bf16 v[24:27], v[238:241], v[206:209], v[24:27]
	v_mfma_f32_16x16x32_bf16 v[16:19], v[230:233], v[214:217], v[16:19]
	v_mfma_f32_16x16x32_bf16 v[8:11], v[238:241], v[214:217], v[8:11]
	v_mfma_f32_16x16x32_bf16 v[4:7], v[230:233], v[222:225], v[4:7]
	v_mfma_f32_16x16x32_bf16 v[0:3], v[238:241], v[222:225], v[0:3]
	s_setprio 0
	s_barrier
	s_add_i32 s21, 0, 0x18000
	v_add_u32_e32 v138, s21, v153
	ds_read_b128 v[158:161], v138
	ds_read_b128 v[182:185], v138 offset:1024
	ds_read_b128 v[186:189], v138 offset:2048
	ds_read_b128 v[190:193], v138 offset:3072
	s_add_u32 s40, s40, 0x80000
	s_addc_u32 s41, s41, 0
	s_mov_b32 m0, s50
	v_lshl_add_u64 v[150:151], s[40:41], 0, v[150:151]
	ds_read_b128 v[194:197], v154 offset:32768
	ds_read_b128 v[198:201], v154 offset:33792
	ds_read_b128 v[202:205], v154 offset:34816
	ds_read_b128 v[206:209], v154 offset:35840
	ds_read_b128 v[210:213], v154 offset:36864
	ds_read_b128 v[214:217], v154 offset:37888
	ds_read_b128 v[218:221], v154 offset:38912
	ds_read_b128 v[222:225], v154 offset:39936
	global_load_lds_dwordx4 v[150:151], off
	v_lshl_add_u64 v[148:149], s[40:41], 0, v[148:149]
	s_mov_b32 m0, s51
	s_nop 0
	global_load_lds_dwordx4 v[148:149], off
	s_waitcnt lgkmcnt(8)
	s_barrier
	s_waitcnt lgkmcnt(0)
	s_setprio 1
	v_mfma_f32_16x16x32_bf16 v[124:127], v[158:161], v[194:197], v[124:127]
	v_mfma_f32_16x16x32_bf16 v[120:123], v[186:189], v[194:197], v[120:123]
	v_mfma_f32_16x16x32_bf16 v[116:119], v[158:161], v[202:205], v[116:119]
	v_mfma_f32_16x16x32_bf16 v[112:115], v[186:189], v[202:205], v[112:115]
	v_mfma_f32_16x16x32_bf16 v[100:103], v[158:161], v[210:213], v[100:103]
	v_mfma_f32_16x16x32_bf16 v[96:99], v[186:189], v[210:213], v[96:99]
	v_mfma_f32_16x16x32_bf16 v[84:87], v[158:161], v[218:221], v[84:87]
	v_mfma_f32_16x16x32_bf16 v[80:83], v[186:189], v[218:221], v[80:83]
	v_mfma_f32_16x16x32_bf16 v[124:127], v[182:185], v[198:201], v[124:127]
	v_mfma_f32_16x16x32_bf16 v[120:123], v[190:193], v[198:201], v[120:123]
	v_mfma_f32_16x16x32_bf16 v[116:119], v[182:185], v[206:209], v[116:119]
	v_mfma_f32_16x16x32_bf16 v[112:115], v[190:193], v[206:209], v[112:115]
	v_mfma_f32_16x16x32_bf16 v[100:103], v[182:185], v[214:217], v[100:103]
	v_mfma_f32_16x16x32_bf16 v[96:99], v[190:193], v[214:217], v[96:99]
	v_mfma_f32_16x16x32_bf16 v[84:87], v[182:185], v[222:225], v[84:87]
	v_mfma_f32_16x16x32_bf16 v[80:83], v[190:193], v[222:225], v[80:83]
	s_setprio 0
	s_barrier
	s_add_i32 s40, 0, 0x1c000
	s_add_i32 s21, s21, s43
	v_add_u32_e32 v138, s40, v153
	v_lshl_add_u64 v[238:239], v[242:243], 0, s[44:45]
	s_mov_b32 m0, s21
	ds_read_b128 v[148:151], v138
	ds_read_b128 v[226:229], v138 offset:1024
	ds_read_b128 v[230:233], v138 offset:2048
	ds_read_b128 v[234:237], v138 offset:3072
	global_load_lds_dwordx4 v[238:239], off
	v_lshl_add_u64 v[238:239], v[244:245], 0, s[44:45]
	s_add_i32 m0, s21, 0x2000
	s_nop 0
	global_load_lds_dwordx4 v[238:239], off
	s_barrier
; #define PG8_STAGE(bufoff, gbase, v0, v1) do { \
;         __builtin_amdgcn_global_load_lds((const unsigned*)((const char*)(gbase) + (v0)), (LAS unsigned*)(lds + (bufoff) + ldsw), 16, 0, 0); \
;         __builtin_amdgcn_global_load_lds((const unsigned*)((const char*)(gbase) + (v1)), (LAS unsigned*)(lds + (bufoff) + ldsw + 8192), 16, 0, 0); } while (0)
; #define PG8_LDA(dst, b, h) do { _Pragma("unroll") for (int m = 0; m < 4; ++m) _Pragma("unroll") for (int k = 0; k < 2; ++k) dst[m][k] = *(const LAS bf16x8*)(lds + PG8_SA(b, h) + aoff + m * 2048 + k * 1024); } while (0)
; #define PG8_MMA(ai, bj, At, Bt) do { __builtin_amdgcn_s_setprio(1); _Pragma("unroll") for (int m = 0; m < 4; ++m) _Pragma("unroll") for (int n = 0; n < 2; ++n) _Pragma("unroll") for (int k = 0; k < 2; ++k) \
;         acc[ai][bj][m][n] = __builtin_amdgcn_mfma_f32_16x16x32_bf16(Bt[n][k], At[m][k], acc[ai][bj][m][n], 0, 0, 0); __builtin_amdgcn_s_setprio(0); } while (0)
; #define PG8_WAIT_V(n) asm volatile("s_waitcnt vmcnt(" #n ")" ::: "memory")
; #define PG8_WAIT_L(n) asm volatile("s_waitcnt lgkmcnt(" #n ")" ::: "memory")
; #define PG8_BAR __builtin_amdgcn_s_barrier()
; #define PG8_SCHED __builtin_amdgcn_sched_barrier(0)
; template <class Epi, class Sched>
; __device__ __forceinline__ void gemm_phase(LAS unsigned char* lds, const Sched& S, const Epi& E) {
;     ...
;         for (int t = 0; t < nt; t += 2) {
;             const bool last = (t == nt - 2);
;             const char* a1 = cA + (size_t)(t + 1) * kstep;
;             const char* a2 = last ? nA : cA + (size_t)(t + 2) * kstep; const char* b2 = last ? nB : cB + (size_t)(t + 2) * kstep;
;             const char* a3 = a2 + kstep; const char* b3 = b2 + kstep;
;             const unsigned xA0 = last ? nvA0 : vA0, xA1 = last ? nvA1 : vA1, xB0 = last ? nvB0 : vB0, xB1 = last ? nvB1 : vB1;
;             const size_t xhA = last ? nhA : hA, xhB = last ? nhB : hB;
;     ...
;             PG8_BAR; PG8_WAIT_L(0); PG8_MMA(0, 1, At, B1); PG8_BAR;
;             PG8_LDA(At, 1, 1); PG8_STAGE(PG8_SA(1, 0), a3, xA0, xA1);
;             PG8_BAR; PG8_WAIT_L(0); PG8_MMA(1, 0, At, B0); PG8_BAR; PG8_SCHED;
;             PG8_STAGE(PG8_SB(1, 1), b3 + xhB, xB0, xB1);
;             PG8_WAIT_V(6); PG8_BAR; PG8_MMA(1, 1, At, B1); PG8_BAR;
	s_waitcnt lgkmcnt(0)
	s_setprio 1
	v_mfma_f32_16x16x32_bf16 v[108:111], v[148:151], v[194:197], v[108:111]
	v_mfma_f32_16x16x32_bf16 v[104:107], v[230:233], v[194:197], v[104:107]
	v_mfma_f32_16x16x32_bf16 v[92:95], v[148:151], v[202:205], v[92:95]
	v_mfma_f32_16x16x32_bf16 v[88:91], v[230:233], v[202:205], v[88:91]
	v_mfma_f32_16x16x32_bf16 v[76:79], v[148:151], v[210:213], v[76:79]
	v_mfma_f32_16x16x32_bf16 v[72:75], v[230:233], v[210:213], v[72:75]
	v_mfma_f32_16x16x32_bf16 v[68:71], v[148:151], v[218:221], v[68:71]
	v_mfma_f32_16x16x32_bf16 v[64:67], v[230:233], v[218:221], v[64:67]
	v_mfma_f32_16x16x32_bf16 v[108:111], v[226:229], v[198:201], v[108:111]
	v_mfma_f32_16x16x32_bf16 v[104:107], v[234:237], v[198:201], v[104:107]
	v_mfma_f32_16x16x32_bf16 v[92:95], v[226:229], v[206:209], v[92:95]
	v_mfma_f32_16x16x32_bf16 v[88:91], v[234:237], v[206:209], v[88:91]
	v_mfma_f32_16x16x32_bf16 v[76:79], v[226:229], v[214:217], v[76:79]
	v_mfma_f32_16x16x32_bf16 v[72:75], v[234:237], v[214:217], v[72:75]
	v_mfma_f32_16x16x32_bf16 v[68:71], v[226:229], v[222:225], v[68:71]
	v_mfma_f32_16x16x32_bf16 v[64:67], v[234:237], v[222:225], v[64:67]
	s_setprio 0
	s_barrier
	s_mov_b32 m0, s64
	v_lshl_add_u64 v[238:239], v[246:247], 0, s[44:45]
	ds_read_b128 v[194:197], v154 offset:49152
	ds_read_b128 v[198:201], v154 offset:50176
	ds_read_b128 v[202:205], v154 offset:51200
	ds_read_b128 v[206:209], v154 offset:52224
	ds_read_b128 v[210:213], v154 offset:53248
	ds_read_b128 v[214:217], v154 offset:54272
	ds_read_b128 v[218:221], v154 offset:55296
	ds_read_b128 v[222:225], v154 offset:56320
	global_load_lds_dwordx4 v[238:239], off
	v_lshl_add_u64 v[238:239], v[248:249], 0, s[44:45]
	s_mov_b32 m0, s65
	s_nop 0
	global_load_lds_dwordx4 v[238:239], off
	s_barrier
	s_waitcnt lgkmcnt(0)
	s_setprio 1
	v_mfma_f32_16x16x32_bf16 v[60:63], v[158:161], v[194:197], v[60:63]
	v_mfma_f32_16x16x32_bf16 v[56:59], v[186:189], v[194:197], v[56:59]
	v_mfma_f32_16x16x32_bf16 v[52:55], v[158:161], v[202:205], v[52:55]
	v_mfma_f32_16x16x32_bf16 v[44:47], v[186:189], v[202:205], v[44:47]
	v_mfma_f32_16x16x32_bf16 v[36:39], v[158:161], v[210:213], v[36:39]
	v_mfma_f32_16x16x32_bf16 v[28:31], v[186:189], v[210:213], v[28:31]
	v_mfma_f32_16x16x32_bf16 v[20:23], v[158:161], v[218:221], v[20:23]
	v_mfma_f32_16x16x32_bf16 v[12:15], v[186:189], v[218:221], v[12:15]
	v_mfma_f32_16x16x32_bf16 v[60:63], v[182:185], v[198:201], v[60:63]
	v_mfma_f32_16x16x32_bf16 v[56:59], v[190:193], v[198:201], v[56:59]
	v_mfma_f32_16x16x32_bf16 v[52:55], v[182:185], v[206:209], v[52:55]
	v_mfma_f32_16x16x32_bf16 v[44:47], v[190:193], v[206:209], v[44:47]
	v_mfma_f32_16x16x32_bf16 v[36:39], v[182:185], v[214:217], v[36:39]
	v_mfma_f32_16x16x32_bf16 v[28:31], v[190:193], v[214:217], v[28:31]
	v_mfma_f32_16x16x32_bf16 v[20:23], v[182:185], v[222:225], v[20:23]
	v_mfma_f32_16x16x32_bf16 v[12:15], v[190:193], v[222:225], v[12:15]
	s_setprio 0
	s_barrier
	s_add_u32 s38, s38, 0x80080
	s_addc_u32 s39, s39, 0
	s_add_i32 s21, s40, s43
	s_mov_b32 m0, s21
	s_nop 0
	global_load_lds_dwordx4 v136, s[38:39]
	s_add_i32 m0, s21, 0x2000
	s_nop 0
	global_load_lds_dwordx4 v146, s[38:39]
	s_waitcnt vmcnt(6)
	s_barrier
	s_setprio 1
	v_mfma_f32_16x16x32_bf16 v[48:51], v[148:151], v[194:197], v[48:51]
	v_mfma_f32_16x16x32_bf16 v[40:43], v[230:233], v[194:197], v[40:43]
	v_mfma_f32_16x16x32_bf16 v[32:35], v[148:151], v[202:205], v[32:35]
	v_mfma_f32_16x16x32_bf16 v[24:27], v[230:233], v[202:205], v[24:27]
	v_mfma_f32_16x16x32_bf16 v[16:19], v[148:151], v[210:213], v[16:19]
	v_mfma_f32_16x16x32_bf16 v[8:11], v[230:233], v[210:213], v[8:11]
	v_mfma_f32_16x16x32_bf16 v[4:7], v[148:151], v[218:221], v[4:7]
	v_mfma_f32_16x16x32_bf16 v[0:3], v[230:233], v[218:221], v[0:3]
	v_mfma_f32_16x16x32_bf16 v[48:51], v[226:229], v[198:201], v[48:51]
	v_mfma_f32_16x16x32_bf16 v[40:43], v[234:237], v[198:201], v[40:43]
	v_mfma_f32_16x16x32_bf16 v[32:35], v[226:229], v[206:209], v[32:35]
	v_mfma_f32_16x16x32_bf16 v[24:27], v[234:237], v[206:209], v[24:27]
	v_mfma_f32_16x16x32_bf16 v[16:19], v[226:229], v[214:217], v[16:19]
	v_mfma_f32_16x16x32_bf16 v[8:11], v[234:237], v[214:217], v[8:11]
	v_mfma_f32_16x16x32_bf16 v[4:7], v[226:229], v[222:225], v[4:7]
	v_mfma_f32_16x16x32_bf16 v[0:3], v[234:237], v[222:225], v[0:3]
	s_setprio 0
	s_add_i32 s15, s15, 2
	s_add_u32 s26, s26, 0x100
	s_addc_u32 s27, s27, 0
	s_add_u32 s34, s34, 0x100
	s_addc_u32 s35, s35, 0
	s_cmp_gt_u32 s15, 29
	s_cbranch_scc1 .Lrot_exit_0
	s_cmp_eq_u32 s15, 28
	s_cselect_b64 s[40:41], -1, 0
	s_and_b64 vcc, exec, s[40:41]
	v_mov_b64_e32 v[148:149], v[130:131]
	v_mov_b64_e32 v[150:151], v[128:129]
	v_mov_b32_e32 v146, v156
	v_mov_b32_e32 v136, v155
	s_mov_b64 s[38:39], s[24:25]
	s_cbranch_vccnz .Lrot_join_0
	v_mov_b64_e32 v[148:149], v[134:135]
	v_mov_b64_e32 v[150:151], v[132:133]
	v_mov_b32_e32 v146, v142
	v_mov_b32_e32 v136, v144
	s_mov_b64 s[38:39], s[34:35]

; #define PG8_STAGE(bufoff, gbase, v0, v1) do { \
;         __builtin_amdgcn_global_load_lds((const unsigned*)((const char*)(gbase) + (v0)), (LAS unsigned*)(lds + (bufoff) + ldsw), 16, 0, 0); \
;         __builtin_amdgcn_global_load_lds((const unsigned*)((const char*)(gbase) + (v1)), (LAS unsigned*)(lds + (bufoff) + ldsw + 8192), 16, 0, 0); } while (0)
; #define PG8_LDA(dst, b, h) do { _Pragma("unroll") for (int m = 0; m < 4; ++m) _Pragma("unroll") for (int k = 0; k < 2; ++k) dst[m][k] = *(const LAS bf16x8*)(lds + PG8_SA(b, h) + aoff + m * 2048 + k * 1024); } while (0)
; #define PG8_LDB(dst, b, h) do { _Pragma("unroll") for (int n = 0; n < 2; ++n) _Pragma("unroll") for (int k = 0; k < 2; ++k) dst[n][k] = *(const LAS bf16x8*)(lds + PG8_SB(b, h) + boff + n * 2048 + k * 1024); } while (0)
; #define PG8_MMA(ai, bj, At, Bt) do { __builtin_amdgcn_s_setprio(1); _Pragma("unroll") for (int m = 0; m < 4; ++m) _Pragma("unroll") for (int n = 0; n < 2; ++n) _Pragma("unroll") for (int k = 0; k < 2; ++k) \
;         acc[ai][bj][m][n] = __builtin_amdgcn_mfma_f32_16x16x32_bf16(Bt[n][k], At[m][k], acc[ai][bj][m][n], 0, 0, 0); __builtin_amdgcn_s_setprio(0); } while (0)
; template <class Epi, class Sched>
; __device__ __forceinline__ void gemm_phase(LAS unsigned char* lds, const Sched& S, const Epi& E) {
;     ...
;         for (int t = 0; t < nt; t += 2) {
;             const bool last = (t == nt - 2);
;             const char* a1 = cA + (size_t)(t + 1) * kstep;
;             const char* a2 = last ? nA : cA + (size_t)(t + 2) * kstep; const char* b2 = last ? nB : cB + (size_t)(t + 2) * kstep;
;             const char* a3 = a2 + kstep; const char* b3 = b2 + kstep;
;             const unsigned xA0 = last ? nvA0 : vA0, xA1 = last ? nvA1 : vA1, xB0 = last ? nvB0 : vB0, xB1 = last ? nvB1 : vB1;
;             const size_t xhA = last ? nhA : hA, xhB = last ? nhB : hB;
;             PG8_LDB(B0, 0, 0); PG8_SCHED; PG8_LDA(At, 0, 0); PG8_STAGE(PG8_SA(1, 1), a1 + hA, vA0, vA1);
;             PG8_WAIT_L(8); PG8_BAR; PG8_WAIT_L(0); PG8_MMA(0, 0, At, B0); PG8_BAR; PG8_SCHED;
;             PG8_LDB(B1, 0, 1); PG8_STAGE(PG8_SB(0, 0), b2, xB0, xB1);
;             PG8_BAR; PG8_WAIT_L(0); PG8_MMA(0, 1, At, B1); PG8_BAR;
;             PG8_LDA(At, 0, 1); PG8_STAGE(PG8_SA(0, 0), a2, xA0, xA1);
;             PG8_BAR; PG8_WAIT_L(0); PG8_MMA(1, 0, At, B0); PG8_BAR; PG8_SCHED;
.LBB0_574:
	s_add_i32 s49, s49, 2
	s_add_u32 s65, s34, 0x80
	s_addc_u32 vcc_lo, s35, 0
	s_and_b64 s[54:55], exec, s[54:55]
	s_cselect_b32 s55, s41, vcc_lo
	s_cselect_b32 s54, s40, s65
	s_add_i32 s65, 0, 0x10000
	v_add_u32_e32 v138, s65, v184
	ds_read_b128 v[158:161], v138
	ds_read_b128 v[186:189], v138 offset:1024
	ds_read_b128 v[190:193], v138 offset:2048
	ds_read_b128 v[194:197], v138 offset:3072
	v_lshl_add_u64 v[230:231], s[34:35], 0, v[134:135]
	s_add_i32 m0, s91, 0xc000
	ds_read_b128 v[198:201], v185
	ds_read_b128 v[202:205], v185 offset:1024
	ds_read_b128 v[206:209], v185 offset:2048
	ds_read_b128 v[210:213], v185 offset:3072
	ds_read_b128 v[214:217], v185 offset:4096
	ds_read_b128 v[218:221], v185 offset:5120
	ds_read_b128 v[222:225], v185 offset:6144
	ds_read_b128 v[226:229], v185 offset:7168
	global_load_lds_dwordx4 v[230:231], off
	v_lshl_add_u64 v[230:231], s[34:35], 0, v[150:151]
	s_add_i32 m0, s91, 0xe000
	s_nop 0
	global_load_lds_dwordx4 v[230:231], off
	s_waitcnt lgkmcnt(8)
	s_barrier
	s_waitcnt lgkmcnt(0)
	s_setprio 1
	v_mfma_f32_16x16x32_bf16 v[124:127], v[158:161], v[198:201], v[124:127]
	v_mfma_f32_16x16x32_bf16 v[120:123], v[190:193], v[198:201], v[120:123]
	v_mfma_f32_16x16x32_bf16 v[116:119], v[158:161], v[206:209], v[116:119]
	v_mfma_f32_16x16x32_bf16 v[112:115], v[190:193], v[206:209], v[112:115]
	v_mfma_f32_16x16x32_bf16 v[108:111], v[158:161], v[214:217], v[108:111]
	v_mfma_f32_16x16x32_bf16 v[104:107], v[190:193], v[214:217], v[104:107]
	v_mfma_f32_16x16x32_bf16 v[100:103], v[158:161], v[222:225], v[100:103]
	v_mfma_f32_16x16x32_bf16 v[96:99], v[190:193], v[222:225], v[96:99]
	v_mfma_f32_16x16x32_bf16 v[124:127], v[186:189], v[202:205], v[124:127]
	v_mfma_f32_16x16x32_bf16 v[120:123], v[194:197], v[202:205], v[120:123]
	v_mfma_f32_16x16x32_bf16 v[116:119], v[186:189], v[210:213], v[116:119]
	v_mfma_f32_16x16x32_bf16 v[112:115], v[194:197], v[210:213], v[112:115]
	v_mfma_f32_16x16x32_bf16 v[108:111], v[186:189], v[218:221], v[108:111]
	v_mfma_f32_16x16x32_bf16 v[104:107], v[194:197], v[218:221], v[104:107]
	v_mfma_f32_16x16x32_bf16 v[100:103], v[186:189], v[226:229], v[100:103]
	v_mfma_f32_16x16x32_bf16 v[96:99], v[194:197], v[226:229], v[96:99]
	s_setprio 0
	s_barrier
	s_add_i32 vcc_lo, 0, 0x14000
	s_add_i32 s65, s65, s9
	v_add_u32_e32 v138, vcc_lo, v184
	s_mov_b32 m0, s65
	ds_read_b128 v[230:233], v138
	ds_read_b128 v[234:237], v138 offset:1024
	ds_read_b128 v[238:241], v138 offset:2048
	ds_read_b128 v[242:245], v138 offset:3072
	global_load_lds_dwordx4 v136, s[92:93]
	s_add_i32 m0, s65, 0x2000
	v_mov_b32_e32 v157, v137
	global_load_lds_dwordx4 v156, s[92:93]
	v_lshl_add_u64 v[246:247], s[92:93], 0, v[136:137]
	v_lshl_add_u64 v[248:249], s[92:93], 0, v[156:157]
	s_barrier
	s_waitcnt lgkmcnt(0)
	s_setprio 1
	v_mfma_f32_16x16x32_bf16 v[92:95], v[230:233], v[198:201], v[92:95]
	v_mfma_f32_16x16x32_bf16 v[88:91], v[238:241], v[198:201], v[88:91]
	v_mfma_f32_16x16x32_bf16 v[84:87], v[230:233], v[206:209], v[84:87]
	v_mfma_f32_16x16x32_bf16 v[80:83], v[238:241], v[206:209], v[80:83]
	v_mfma_f32_16x16x32_bf16 v[76:79], v[230:233], v[214:217], v[76:79]
	v_mfma_f32_16x16x32_bf16 v[72:75], v[238:241], v[214:217], v[72:75]
	v_mfma_f32_16x16x32_bf16 v[68:71], v[230:233], v[222:225], v[68:71]
	v_mfma_f32_16x16x32_bf16 v[64:67], v[238:241], v[222:225], v[64:67]
	v_mfma_f32_16x16x32_bf16 v[92:95], v[234:237], v[202:205], v[92:95]
	v_mfma_f32_16x16x32_bf16 v[88:91], v[242:245], v[202:205], v[88:91]
	v_mfma_f32_16x16x32_bf16 v[84:87], v[234:237], v[210:213], v[84:87]
	v_mfma_f32_16x16x32_bf16 v[80:83], v[242:245], v[210:213], v[80:83]
	v_mfma_f32_16x16x32_bf16 v[76:79], v[234:237], v[218:221], v[76:79]
	v_mfma_f32_16x16x32_bf16 v[72:75], v[242:245], v[218:221], v[72:75]
	v_mfma_f32_16x16x32_bf16 v[68:71], v[234:237], v[226:229], v[68:71]
	v_mfma_f32_16x16x32_bf16 v[64:67], v[242:245], v[226:229], v[64:67]
	s_setprio 0
	s_barrier
	s_mov_b32 m0, s91
	v_lshl_add_u64 v[250:251], s[54:55], 0, v[154:155]
	ds_read_b128 v[198:201], v185 offset:16384
	ds_read_b128 v[202:205], v185 offset:17408
	ds_read_b128 v[206:209], v185 offset:18432
	ds_read_b128 v[210:213], v185 offset:19456
	ds_read_b128 v[214:217], v185 offset:20480
	ds_read_b128 v[218:221], v185 offset:21504
	ds_read_b128 v[222:225], v185 offset:22528
	ds_read_b128 v[226:229], v185 offset:23552
	global_load_lds_dwordx4 v[250:251], off
	v_lshl_add_u64 v[140:141], s[54:55], 0, v[152:153]
	s_mov_b32 m0, s50
	s_nop 0
	global_load_lds_dwordx4 v[140:141], off
	s_barrier
	s_waitcnt lgkmcnt(0)
	s_setprio 1
	v_mfma_f32_16x16x32_bf16 v[60:63], v[158:161], v[198:201], v[60:63]
	v_mfma_f32_16x16x32_bf16 v[56:59], v[190:193], v[198:201], v[56:59]
	v_mfma_f32_16x16x32_bf16 v[52:55], v[158:161], v[206:209], v[52:55]
	v_mfma_f32_16x16x32_bf16 v[48:51], v[190:193], v[206:209], v[48:51]
	v_mfma_f32_16x16x32_bf16 v[44:47], v[158:161], v[214:217], v[44:47]
	v_mfma_f32_16x16x32_bf16 v[40:43], v[190:193], v[214:217], v[40:43]
	v_mfma_f32_16x16x32_bf16 v[36:39], v[158:161], v[222:225], v[36:39]
	v_mfma_f32_16x16x32_bf16 v[32:35], v[190:193], v[222:225], v[32:35]
	v_mfma_f32_16x16x32_bf16 v[60:63], v[186:189], v[202:205], v[60:63]
	v_mfma_f32_16x16x32_bf16 v[56:59], v[194:197], v[202:205], v[56:59]
	v_mfma_f32_16x16x32_bf16 v[52:55], v[186:189], v[210:213], v[52:55]
	v_mfma_f32_16x16x32_bf16 v[48:51], v[194:197], v[210:213], v[48:51]
	v_mfma_f32_16x16x32_bf16 v[44:47], v[186:189], v[218:221], v[44:47]
	v_mfma_f32_16x16x32_bf16 v[40:43], v[194:197], v[218:221], v[40:43]
	v_mfma_f32_16x16x32_bf16 v[36:39], v[186:189], v[226:229], v[36:39]
	v_mfma_f32_16x16x32_bf16 v[32:35], v[194:197], v[226:229], v[32:35]
	s_setprio 0
	s_barrier
; #define PG8_STAGE(bufoff, gbase, v0, v1) do { \
;         __builtin_amdgcn_global_load_lds((const unsigned*)((const char*)(gbase) + (v0)), (LAS unsigned*)(lds + (bufoff) + ldsw), 16, 0, 0); \
;         __builtin_amdgcn_global_load_lds((const unsigned*)((const char*)(gbase) + (v1)), (LAS unsigned*)(lds + (bufoff) + ldsw + 8192), 16, 0, 0); } while (0)
; #define PG8_LDA(dst, b, h) do { _Pragma("unroll") for (int m = 0; m < 4; ++m) _Pragma("unroll") for (int k = 0; k < 2; ++k) dst[m][k] = *(const LAS bf16x8*)(lds + PG8_SA(b, h) + aoff + m * 2048 + k * 1024); } while (0)
; #define PG8_LDB(dst, b, h) do { _Pragma("unroll") for (int n = 0; n < 2; ++n) _Pragma("unroll") for (int k = 0; k < 2; ++k) dst[n][k] = *(const LAS bf16x8*)(lds + PG8_SB(b, h) + boff + n * 2048 + k * 1024); } while (0)
; #define PG8_MMA(ai, bj, At, Bt) do { __builtin_amdgcn_s_setprio(1); _Pragma("unroll") for (int m = 0; m < 4; ++m) _Pragma("unroll") for (int n = 0; n < 2; ++n) _Pragma("unroll") for (int k = 0; k < 2; ++k) \
;         acc[ai][bj][m][n] = __builtin_amdgcn_mfma_f32_16x16x32_bf16(Bt[n][k], At[m][k], acc[ai][bj][m][n], 0, 0, 0); __builtin_amdgcn_s_setprio(0); } while (0)
; #define PG8_WAIT_V(n) asm volatile("s_waitcnt vmcnt(" #n ")" ::: "memory")
; #define PG8_WAIT_L(n) asm volatile("s_waitcnt lgkmcnt(" #n ")" ::: "memory")
; #define PG8_BAR __builtin_amdgcn_s_barrier()
; #define PG8_SCHED __builtin_amdgcn_sched_barrier(0)
; template <class Epi, class Sched>
; __device__ __forceinline__ void gemm_phase(LAS unsigned char* lds, const Sched& S, const Epi& E) {
;     ...
;             PG8_STAGE(PG8_SB(0, 1), b2 + xhB, xB0, xB1);
;             PG8_WAIT_V(6); PG8_BAR; PG8_MMA(1, 1, At, B1); PG8_BAR;
;             PG8_LDB(B0, 1, 0); PG8_SCHED; PG8_LDA(At, 1, 0); PG8_STAGE(PG8_SA(0, 1), a2 + xhA, xA0, xA1);
;             PG8_WAIT_L(8); PG8_BAR; PG8_WAIT_L(0); PG8_MMA(0, 0, At, B0); PG8_BAR; PG8_SCHED;
;             PG8_LDB(B1, 1, 1); PG8_STAGE(PG8_SB(1, 0), b3, xB0, xB1);
;             PG8_BAR; PG8_WAIT_L(0); PG8_MMA(0, 1, At, B1); PG8_BAR;
	s_add_u32 s88, s92, s88
	s_addc_u32 s89, s93, s89
	s_add_i32 s65, vcc_lo, s9
	s_mov_b32 m0, s65
	v_lshl_add_u64 v[160:161], s[88:89], 0, v[136:137]
	global_load_lds_dwordx4 v136, s[88:89]
	s_add_i32 m0, s65, 0x2000
	v_lshl_add_u64 v[138:139], s[88:89], 0, v[156:157]
	global_load_lds_dwordx4 v156, s[88:89]
	s_waitcnt vmcnt(6)
	s_barrier
	s_setprio 1
	v_mfma_f32_16x16x32_bf16 v[28:31], v[230:233], v[198:201], v[28:31]
	v_mfma_f32_16x16x32_bf16 v[24:27], v[238:241], v[198:201], v[24:27]
	v_mfma_f32_16x16x32_bf16 v[20:23], v[230:233], v[206:209], v[20:23]
	v_mfma_f32_16x16x32_bf16 v[16:19], v[238:241], v[206:209], v[16:19]
	v_mfma_f32_16x16x32_bf16 v[12:15], v[230:233], v[214:217], v[12:15]
	v_mfma_f32_16x16x32_bf16 v[8:11], v[238:241], v[214:217], v[8:11]
	v_mfma_f32_16x16x32_bf16 v[4:7], v[230:233], v[222:225], v[4:7]
	v_mfma_f32_16x16x32_bf16 v[0:3], v[238:241], v[222:225], v[0:3]
	v_mfma_f32_16x16x32_bf16 v[28:31], v[234:237], v[202:205], v[28:31]
	v_mfma_f32_16x16x32_bf16 v[24:27], v[242:245], v[202:205], v[24:27]
	v_mfma_f32_16x16x32_bf16 v[20:23], v[234:237], v[210:213], v[20:23]
	v_mfma_f32_16x16x32_bf16 v[16:19], v[242:245], v[210:213], v[16:19]
	v_mfma_f32_16x16x32_bf16 v[12:15], v[234:237], v[218:221], v[12:15]
	v_mfma_f32_16x16x32_bf16 v[8:11], v[242:245], v[218:221], v[8:11]
	v_mfma_f32_16x16x32_bf16 v[4:7], v[234:237], v[226:229], v[4:7]
	v_mfma_f32_16x16x32_bf16 v[0:3], v[242:245], v[226:229], v[0:3]
	s_setprio 0
	s_barrier
	s_add_i32 s65, 0, 0x18000
	v_add_u32_e32 v136, s65, v184
	ds_read_b128 v[156:159], v136
	ds_read_b128 v[186:189], v136 offset:1024
	ds_read_b128 v[190:193], v136 offset:2048
	ds_read_b128 v[194:197], v136 offset:3072
	s_add_u32 s54, s54, s82
	s_addc_u32 s55, s55, s83
	s_mov_b32 m0, s51
	v_lshl_add_u64 v[154:155], s[54:55], 0, v[154:155]
	ds_read_b128 v[198:201], v185 offset:32768
	ds_read_b128 v[202:205], v185 offset:33792
	ds_read_b128 v[206:209], v185 offset:34816
	ds_read_b128 v[210:213], v185 offset:35840
	ds_read_b128 v[214:217], v185 offset:36864
	ds_read_b128 v[218:221], v185 offset:37888
	ds_read_b128 v[222:225], v185 offset:38912
	ds_read_b128 v[226:229], v185 offset:39936
	global_load_lds_dwordx4 v[154:155], off
	v_lshl_add_u64 v[152:153], s[54:55], 0, v[152:153]
	s_mov_b32 m0, s8
	s_nop 0
	global_load_lds_dwordx4 v[152:153], off
	s_waitcnt lgkmcnt(8)
	s_barrier
	s_waitcnt lgkmcnt(0)
	s_setprio 1
	v_mfma_f32_16x16x32_bf16 v[124:127], v[156:159], v[198:201], v[124:127]
	v_mfma_f32_16x16x32_bf16 v[120:123], v[190:193], v[198:201], v[120:123]
	v_mfma_f32_16x16x32_bf16 v[116:119], v[156:159], v[206:209], v[116:119]
	v_mfma_f32_16x16x32_bf16 v[112:115], v[190:193], v[206:209], v[112:115]
	v_mfma_f32_16x16x32_bf16 v[108:111], v[156:159], v[214:217], v[108:111]
	v_mfma_f32_16x16x32_bf16 v[104:107], v[190:193], v[214:217], v[104:107]
	v_mfma_f32_16x16x32_bf16 v[100:103], v[156:159], v[222:225], v[100:103]
	v_mfma_f32_16x16x32_bf16 v[96:99], v[190:193], v[222:225], v[96:99]
	v_mfma_f32_16x16x32_bf16 v[124:127], v[186:189], v[202:205], v[124:127]
	v_mfma_f32_16x16x32_bf16 v[120:123], v[194:197], v[202:205], v[120:123]
	v_mfma_f32_16x16x32_bf16 v[116:119], v[186:189], v[210:213], v[116:119]
	v_mfma_f32_16x16x32_bf16 v[112:115], v[194:197], v[210:213], v[112:115]
	v_mfma_f32_16x16x32_bf16 v[108:111], v[186:189], v[218:221], v[108:111]
	v_mfma_f32_16x16x32_bf16 v[104:107], v[194:197], v[218:221], v[104:107]
	v_mfma_f32_16x16x32_bf16 v[100:103], v[186:189], v[226:229], v[100:103]
	v_mfma_f32_16x16x32_bf16 v[96:99], v[194:197], v[226:229], v[96:99]
	s_setprio 0
	s_barrier
	s_add_i32 s54, 0, 0x1c000
	s_add_i32 s55, s65, s9
	v_add_u32_e32 v136, s54, v184
	v_lshl_add_u64 v[242:243], v[246:247], 0, s[44:45]
	s_mov_b32 m0, s55
	ds_read_b128 v[152:155], v136
	ds_read_b128 v[230:233], v136 offset:1024
	ds_read_b128 v[234:237], v136 offset:2048
	ds_read_b128 v[238:241], v136 offset:3072
	global_load_lds_dwordx4 v[242:243], off
	v_lshl_add_u64 v[242:243], v[248:249], 0, s[44:45]
	s_add_i32 m0, s55, 0x2000
	s_nop 0
	global_load_lds_dwordx4 v[242:243], off
	s_barrier
; #define PG8_STAGE(bufoff, gbase, v0, v1) do { \
;         __builtin_amdgcn_global_load_lds((const unsigned*)((const char*)(gbase) + (v0)), (LAS unsigned*)(lds + (bufoff) + ldsw), 16, 0, 0); \
;         __builtin_amdgcn_global_load_lds((const unsigned*)((const char*)(gbase) + (v1)), (LAS unsigned*)(lds + (bufoff) + ldsw + 8192), 16, 0, 0); } while (0)
; #define PG8_LDA(dst, b, h) do { _Pragma("unroll") for (int m = 0; m < 4; ++m) _Pragma("unroll") for (int k = 0; k < 2; ++k) dst[m][k] = *(const LAS bf16x8*)(lds + PG8_SA(b, h) + aoff + m * 2048 + k * 1024); } while (0)
; #define PG8_MMA(ai, bj, At, Bt) do { __builtin_amdgcn_s_setprio(1); _Pragma("unroll") for (int m = 0; m < 4; ++m) _Pragma("unroll") for (int n = 0; n < 2; ++n) _Pragma("unroll") for (int k = 0; k < 2; ++k) \
;         acc[ai][bj][m][n] = __builtin_amdgcn_mfma_f32_16x16x32_bf16(Bt[n][k], At[m][k], acc[ai][bj][m][n], 0, 0, 0); __builtin_amdgcn_s_setprio(0); } while (0)
; #define PG8_WAIT_V(n) asm volatile("s_waitcnt vmcnt(" #n ")" ::: "memory")
; #define PG8_WAIT_L(n) asm volatile("s_waitcnt lgkmcnt(" #n ")" ::: "memory")
; #define PG8_BAR __builtin_amdgcn_s_barrier()
; #define PG8_SCHED __builtin_amdgcn_sched_barrier(0)
; template <class Epi, class Sched>
; __device__ __forceinline__ void gemm_phase(LAS unsigned char* lds, const Sched& S, const Epi& E) {
;     ...
;             const bool last = (t == nt - 2);
;             const char* a1 = cA + (size_t)(t + 1) * kstep;
;             const char* a2 = last ? nA : cA + (size_t)(t + 2) * kstep; const char* b2 = last ? nB : cB + (size_t)(t + 2) * kstep;
;             const char* a3 = a2 + kstep; const char* b3 = b2 + kstep;
;             const unsigned xA0 = last ? nvA0 : vA0, xA1 = last ? nvA1 : vA1, xB0 = last ? nvB0 : vB0, xB1 = last ? nvB1 : vB1;
;             const size_t xhA = last ? nhA : hA, xhB = last ? nhB : hB;
;     ...
;             PG8_BAR; PG8_WAIT_L(0); PG8_MMA(0, 1, At, B1); PG8_BAR;
;             PG8_LDA(At, 1, 1); PG8_STAGE(PG8_SA(1, 0), a3, xA0, xA1);
;             PG8_BAR; PG8_WAIT_L(0); PG8_MMA(1, 0, At, B0); PG8_BAR; PG8_SCHED;
;             PG8_STAGE(PG8_SB(1, 1), b3 + xhB, xB0, xB1);
;             PG8_WAIT_V(6); PG8_BAR; PG8_MMA(1, 1, At, B1); PG8_BAR;
;         }
	s_waitcnt lgkmcnt(0)
	s_setprio 1
	v_mfma_f32_16x16x32_bf16 v[92:95], v[152:155], v[198:201], v[92:95]
	v_mfma_f32_16x16x32_bf16 v[88:91], v[234:237], v[198:201], v[88:91]
	v_mfma_f32_16x16x32_bf16 v[84:87], v[152:155], v[206:209], v[84:87]
	v_mfma_f32_16x16x32_bf16 v[80:83], v[234:237], v[206:209], v[80:83]
	v_mfma_f32_16x16x32_bf16 v[76:79], v[152:155], v[214:217], v[76:79]
	v_mfma_f32_16x16x32_bf16 v[72:75], v[234:237], v[214:217], v[72:75]
	v_mfma_f32_16x16x32_bf16 v[68:71], v[152:155], v[222:225], v[68:71]
	v_mfma_f32_16x16x32_bf16 v[64:67], v[234:237], v[222:225], v[64:67]
	v_mfma_f32_16x16x32_bf16 v[92:95], v[230:233], v[202:205], v[92:95]
	v_mfma_f32_16x16x32_bf16 v[88:91], v[238:241], v[202:205], v[88:91]
	v_mfma_f32_16x16x32_bf16 v[84:87], v[230:233], v[210:213], v[84:87]
	v_mfma_f32_16x16x32_bf16 v[80:83], v[238:241], v[210:213], v[80:83]
	v_mfma_f32_16x16x32_bf16 v[76:79], v[230:233], v[218:221], v[76:79]
	v_mfma_f32_16x16x32_bf16 v[72:75], v[238:241], v[218:221], v[72:75]
	v_mfma_f32_16x16x32_bf16 v[68:71], v[230:233], v[226:229], v[68:71]
	v_mfma_f32_16x16x32_bf16 v[64:67], v[238:241], v[226:229], v[64:67]
	s_setprio 0
	s_barrier
	s_mov_b32 m0, s21
	v_lshl_add_u64 v[242:243], v[250:251], 0, s[44:45]
	ds_read_b128 v[198:201], v185 offset:49152
	ds_read_b128 v[202:205], v185 offset:50176
	ds_read_b128 v[206:209], v185 offset:51200
	ds_read_b128 v[210:213], v185 offset:52224
	ds_read_b128 v[214:217], v185 offset:53248
	ds_read_b128 v[218:221], v185 offset:54272
	ds_read_b128 v[222:225], v185 offset:55296
	ds_read_b128 v[226:229], v185 offset:56320
	global_load_lds_dwordx4 v[242:243], off
	v_lshl_add_u64 v[140:141], v[140:141], 0, s[44:45]
	s_mov_b32 m0, s24
	s_nop 0
	global_load_lds_dwordx4 v[140:141], off
	s_barrier
	s_waitcnt lgkmcnt(0)
	s_setprio 1
	v_mfma_f32_16x16x32_bf16 v[60:63], v[156:159], v[198:201], v[60:63]
	v_mfma_f32_16x16x32_bf16 v[56:59], v[190:193], v[198:201], v[56:59]
	v_mfma_f32_16x16x32_bf16 v[52:55], v[156:159], v[206:209], v[52:55]
	v_mfma_f32_16x16x32_bf16 v[48:51], v[190:193], v[206:209], v[48:51]
	v_mfma_f32_16x16x32_bf16 v[44:47], v[156:159], v[214:217], v[44:47]
	v_mfma_f32_16x16x32_bf16 v[40:43], v[190:193], v[214:217], v[40:43]
	v_mfma_f32_16x16x32_bf16 v[36:39], v[156:159], v[222:225], v[36:39]
	v_mfma_f32_16x16x32_bf16 v[32:35], v[190:193], v[222:225], v[32:35]
	v_mfma_f32_16x16x32_bf16 v[60:63], v[186:189], v[202:205], v[60:63]
	v_mfma_f32_16x16x32_bf16 v[56:59], v[194:197], v[202:205], v[56:59]
	v_mfma_f32_16x16x32_bf16 v[52:55], v[186:189], v[210:213], v[52:55]
	v_mfma_f32_16x16x32_bf16 v[48:51], v[194:197], v[210:213], v[48:51]
	v_mfma_f32_16x16x32_bf16 v[44:47], v[186:189], v[218:221], v[44:47]
	v_mfma_f32_16x16x32_bf16 v[40:43], v[194:197], v[218:221], v[40:43]
	v_mfma_f32_16x16x32_bf16 v[36:39], v[186:189], v[226:229], v[36:39]
	v_mfma_f32_16x16x32_bf16 v[32:35], v[194:197], v[226:229], v[32:35]
	s_setprio 0
	s_barrier
	s_add_i32 s54, s54, s9
	v_lshl_add_u64 v[140:141], v[160:161], 0, s[44:45]
	s_mov_b32 m0, s54
	v_lshl_add_u64 v[138:139], v[138:139], 0, s[44:45]
	global_load_lds_dwordx4 v[140:141], off
	s_add_i32 m0, s54, 0x2000
	s_nop 0
	global_load_lds_dwordx4 v[138:139], off
	s_waitcnt vmcnt(6)
	s_barrier
	s_setprio 1
	v_mfma_f32_16x16x32_bf16 v[28:31], v[152:155], v[198:201], v[28:31]
	v_mfma_f32_16x16x32_bf16 v[24:27], v[234:237], v[198:201], v[24:27]
	v_mfma_f32_16x16x32_bf16 v[20:23], v[152:155], v[206:209], v[20:23]
	v_mfma_f32_16x16x32_bf16 v[16:19], v[234:237], v[206:209], v[16:19]
	v_mfma_f32_16x16x32_bf16 v[12:15], v[152:155], v[214:217], v[12:15]
	v_mfma_f32_16x16x32_bf16 v[8:11], v[234:237], v[214:217], v[8:11]
	v_mfma_f32_16x16x32_bf16 v[4:7], v[152:155], v[222:225], v[4:7]
	v_mfma_f32_16x16x32_bf16 v[0:3], v[234:237], v[222:225], v[0:3]
	v_mfma_f32_16x16x32_bf16 v[28:31], v[230:233], v[202:205], v[28:31]
	v_mfma_f32_16x16x32_bf16 v[24:27], v[238:241], v[202:205], v[24:27]
	v_mfma_f32_16x16x32_bf16 v[20:23], v[230:233], v[210:213], v[20:23]
	v_mfma_f32_16x16x32_bf16 v[16:19], v[238:241], v[210:213], v[16:19]
	v_mfma_f32_16x16x32_bf16 v[12:15], v[230:233], v[218:221], v[12:15]
	v_mfma_f32_16x16x32_bf16 v[8:11], v[238:241], v[218:221], v[8:11]
	v_mfma_f32_16x16x32_bf16 v[4:7], v[230:233], v[226:229], v[4:7]
	v_mfma_f32_16x16x32_bf16 v[0:3], v[238:241], v[226:229], v[0:3]
	s_setprio 0
	s_add_u32 s34, s34, 0x100
	s_addc_u32 s35, s35, 0
	s_add_u32 s70, s70, 0x100
	s_addc_u32 s71, s71, 0
	s_cmp_ge_i32 s49, s36
	s_cbranch_scc1 .Lrot_exit_1
	s_cmp_eq_u32 s39, s49
	s_cselect_b64 s[54:55], -1, 0
	s_and_b64 vcc, exec, s[54:55]
	v_mov_b64_e32 v[152:153], v[144:145]
	v_mov_b64_e32 v[154:155], v[142:143]
	s_mov_b64 s[88:89], s[68:69]
	s_mov_b64 s[82:83], s[66:67]
	v_mov_b32_e32 v156, v148
	v_mov_b32_e32 v136, v146
	s_mov_b64 s[92:93], s[42:43]
	s_cbranch_vccnz .Lrot_join_1
	v_mov_b64_e32 v[152:153], v[128:129]
	v_mov_b64_e32 v[154:155], v[132:133]
	s_mov_b64 s[88:89], s[12:13]
	s_mov_b64 s[82:83], s[14:15]
	v_mov_b32_e32 v156, v130
	v_mov_b32_e32 v136, v131
	s_mov_b64 s[92:93], s[70:71]

; #define PG8_STAGE(bufoff, gbase, v0, v1) do { \
;         __builtin_amdgcn_global_load_lds((const unsigned*)((const char*)(gbase) + (v0)), (LAS unsigned*)(lds + (bufoff) + ldsw), 16, 0, 0); \
;         __builtin_amdgcn_global_load_lds((const unsigned*)((const char*)(gbase) + (v1)), (LAS unsigned*)(lds + (bufoff) + ldsw + 8192), 16, 0, 0); } while (0)
; #define PG8_LDA(dst, b, h) do { _Pragma("unroll") for (int m = 0; m < 4; ++m) _Pragma("unroll") for (int k = 0; k < 2; ++k) dst[m][k] = *(const LAS bf16x8*)(lds + PG8_SA(b, h) + aoff + m * 2048 + k * 1024); } while (0)
; #define PG8_LDB(dst, b, h) do { _Pragma("unroll") for (int n = 0; n < 2; ++n) _Pragma("unroll") for (int k = 0; k < 2; ++k) dst[n][k] = *(const LAS bf16x8*)(lds + PG8_SB(b, h) + boff + n * 2048 + k * 1024); } while (0)
; #define PG8_MMA(ai, bj, At, Bt) do { __builtin_amdgcn_s_setprio(1); _Pragma("unroll") for (int m = 0; m < 4; ++m) _Pragma("unroll") for (int n = 0; n < 2; ++n) _Pragma("unroll") for (int k = 0; k < 2; ++k) \
;         acc[ai][bj][m][n] = __builtin_amdgcn_mfma_f32_16x16x32_bf16(Bt[n][k], At[m][k], acc[ai][bj][m][n], 0, 0, 0); __builtin_amdgcn_s_setprio(0); } while (0)
; template <class Epi, class Sched>
; __device__ __forceinline__ void gemm_phase(LAS unsigned char* lds, const Sched& S, const Epi& E) {
;     ...
;         for (int t = 0; t < nt; t += 2) {
;             const bool last = (t == nt - 2);
;             const char* a1 = cA + (size_t)(t + 1) * kstep;
;             const char* a2 = last ? nA : cA + (size_t)(t + 2) * kstep; const char* b2 = last ? nB : cB + (size_t)(t + 2) * kstep;
;             const char* a3 = a2 + kstep; const char* b3 = b2 + kstep;
;             const unsigned xA0 = last ? nvA0 : vA0, xA1 = last ? nvA1 : vA1, xB0 = last ? nvB0 : vB0, xB1 = last ? nvB1 : vB1;
;             const size_t xhA = last ? nhA : hA, xhB = last ? nhB : hB;
;             PG8_LDB(B0, 0, 0); PG8_SCHED; PG8_LDA(At, 0, 0); PG8_STAGE(PG8_SA(1, 1), a1 + hA, vA0, vA1);
;             PG8_WAIT_L(8); PG8_BAR; PG8_WAIT_L(0); PG8_MMA(0, 0, At, B0); PG8_BAR; PG8_SCHED;
;             PG8_LDB(B1, 0, 1); PG8_STAGE(PG8_SB(0, 0), b2, xB0, xB1);
;             PG8_BAR; PG8_WAIT_L(0); PG8_MMA(0, 1, At, B1); PG8_BAR;
;             PG8_LDA(At, 0, 1); PG8_STAGE(PG8_SA(0, 0), a2, xA0, xA1);
;             PG8_BAR; PG8_WAIT_L(0); PG8_MMA(1, 0, At, B0); PG8_BAR; PG8_SCHED;
.LBB0_745:
	s_add_u32 s23, s34, 0xfff80080
	s_addc_u32 s71, s35, -1
	s_and_b64 s[42:43], exec, s[42:43]
	s_cselect_b32 s43, s25, s71
	s_cselect_b32 s42, s24, s23
	s_add_i32 s23, 0, 0x10000
	v_add_u32_e32 v138, s23, v147
	ds_read_b128 v[150:153], v138
	ds_read_b128 v[154:157], v138 offset:1024
	ds_read_b128 v[158:161], v138 offset:2048
	ds_read_b128 v[182:185], v138 offset:3072
	v_lshl_add_u64 v[138:139], s[34:35], 0, v[136:137]
	s_add_i32 m0, s50, 0xc000
	ds_read_b128 v[186:189], v148
	ds_read_b128 v[190:193], v148 offset:1024
	ds_read_b128 v[194:197], v148 offset:2048
	ds_read_b128 v[198:201], v148 offset:3072
	ds_read_b128 v[202:205], v148 offset:4096
	ds_read_b128 v[206:209], v148 offset:5120
	ds_read_b128 v[210:213], v148 offset:6144
	ds_read_b128 v[214:217], v148 offset:7168
	global_load_lds_dwordx4 v[138:139], off
	v_lshl_add_u64 v[138:139], s[34:35], 0, v[132:133]
	s_add_i32 m0, s50, 0xe000
	s_nop 0
	global_load_lds_dwordx4 v[138:139], off
	s_waitcnt lgkmcnt(8)
	s_barrier
	s_waitcnt lgkmcnt(0)
	s_setprio 1
	v_mfma_f32_16x16x32_bf16 v[124:127], v[150:153], v[186:189], v[124:127]
	v_mfma_f32_16x16x32_bf16 v[120:123], v[158:161], v[186:189], v[120:123]
	v_mfma_f32_16x16x32_bf16 v[108:111], v[150:153], v[194:197], v[108:111]
	v_mfma_f32_16x16x32_bf16 v[104:107], v[158:161], v[194:197], v[104:107]
	v_mfma_f32_16x16x32_bf16 v[92:95], v[150:153], v[202:205], v[92:95]
	v_mfma_f32_16x16x32_bf16 v[88:91], v[158:161], v[202:205], v[88:91]
	v_mfma_f32_16x16x32_bf16 v[76:79], v[150:153], v[210:213], v[76:79]
	v_mfma_f32_16x16x32_bf16 v[72:75], v[158:161], v[210:213], v[72:75]
	v_mfma_f32_16x16x32_bf16 v[124:127], v[154:157], v[190:193], v[124:127]
	v_mfma_f32_16x16x32_bf16 v[120:123], v[182:185], v[190:193], v[120:123]
	v_mfma_f32_16x16x32_bf16 v[108:111], v[154:157], v[198:201], v[108:111]
	v_mfma_f32_16x16x32_bf16 v[104:107], v[182:185], v[198:201], v[104:107]
	v_mfma_f32_16x16x32_bf16 v[92:95], v[154:157], v[206:209], v[92:95]
	v_mfma_f32_16x16x32_bf16 v[88:91], v[182:185], v[206:209], v[88:91]
	v_mfma_f32_16x16x32_bf16 v[76:79], v[154:157], v[214:217], v[76:79]
	v_mfma_f32_16x16x32_bf16 v[72:75], v[182:185], v[214:217], v[72:75]
	s_setprio 0
	s_barrier
	s_add_i32 s71, 0, 0x14000
	v_add_u32_e32 v138, s71, v147
	s_add_i32 s23, s23, s49
	ds_read_b128 v[218:221], v138
	ds_read_b128 v[222:225], v138 offset:1024
	ds_read_b128 v[226:229], v138 offset:2048
	ds_read_b128 v[230:233], v138 offset:3072
	v_lshl_add_u64 v[138:139], s[40:41], 0, v[142:143]
	s_mov_b32 m0, s23
	v_lshl_add_u64 v[140:141], s[40:41], 0, v[134:135]
	global_load_lds_dwordx4 v[138:139], off
	s_add_i32 m0, s23, 0x2000
	s_nop 0
	global_load_lds_dwordx4 v[140:141], off
	s_barrier
	s_waitcnt lgkmcnt(0)
	s_setprio 1
	v_mfma_f32_16x16x32_bf16 v[116:119], v[218:221], v[186:189], v[116:119]
	v_mfma_f32_16x16x32_bf16 v[112:115], v[226:229], v[186:189], v[112:115]
	v_mfma_f32_16x16x32_bf16 v[100:103], v[218:221], v[194:197], v[100:103]
	v_mfma_f32_16x16x32_bf16 v[96:99], v[226:229], v[194:197], v[96:99]
	v_mfma_f32_16x16x32_bf16 v[84:87], v[218:221], v[202:205], v[84:87]
	v_mfma_f32_16x16x32_bf16 v[80:83], v[226:229], v[202:205], v[80:83]
	v_mfma_f32_16x16x32_bf16 v[68:71], v[218:221], v[210:213], v[68:71]
	v_mfma_f32_16x16x32_bf16 v[64:67], v[226:229], v[210:213], v[64:67]
	v_mfma_f32_16x16x32_bf16 v[116:119], v[222:225], v[190:193], v[116:119]
	v_mfma_f32_16x16x32_bf16 v[112:115], v[230:233], v[190:193], v[112:115]
	v_mfma_f32_16x16x32_bf16 v[100:103], v[222:225], v[198:201], v[100:103]
	v_mfma_f32_16x16x32_bf16 v[96:99], v[230:233], v[198:201], v[96:99]
	v_mfma_f32_16x16x32_bf16 v[84:87], v[222:225], v[206:209], v[84:87]
	v_mfma_f32_16x16x32_bf16 v[80:83], v[230:233], v[206:209], v[80:83]
	v_mfma_f32_16x16x32_bf16 v[68:71], v[222:225], v[214:217], v[68:71]
	v_mfma_f32_16x16x32_bf16 v[64:67], v[230:233], v[214:217], v[64:67]
	s_setprio 0
	s_barrier
	s_mov_b32 m0, s50
	v_lshl_add_u64 v[234:235], s[42:43], 0, v[142:143]
	ds_read_b128 v[186:189], v148 offset:16384
	ds_read_b128 v[190:193], v148 offset:17408
	ds_read_b128 v[194:197], v148 offset:18432
	ds_read_b128 v[198:201], v148 offset:19456
	ds_read_b128 v[202:205], v148 offset:20480
	ds_read_b128 v[206:209], v148 offset:21504
	ds_read_b128 v[210:213], v148 offset:22528
	ds_read_b128 v[214:217], v148 offset:23552
	global_load_lds_dwordx4 v[234:235], off
	v_lshl_add_u64 v[236:237], s[42:43], 0, v[134:135]
	s_mov_b32 m0, s51
	s_nop 0
	global_load_lds_dwordx4 v[236:237], off
	s_barrier
	s_waitcnt lgkmcnt(0)
	s_setprio 1
	v_mfma_f32_16x16x32_bf16 v[60:63], v[150:153], v[186:189], v[60:63]
	v_mfma_f32_16x16x32_bf16 v[56:59], v[158:161], v[186:189], v[56:59]
	v_mfma_f32_16x16x32_bf16 v[44:47], v[150:153], v[194:197], v[44:47]
	v_mfma_f32_16x16x32_bf16 v[40:43], v[158:161], v[194:197], v[40:43]
	v_mfma_f32_16x16x32_bf16 v[28:31], v[150:153], v[202:205], v[28:31]
	v_mfma_f32_16x16x32_bf16 v[24:27], v[158:161], v[202:205], v[24:27]
	v_mfma_f32_16x16x32_bf16 v[12:15], v[150:153], v[210:213], v[12:15]
	v_mfma_f32_16x16x32_bf16 v[8:11], v[158:161], v[210:213], v[8:11]
	v_mfma_f32_16x16x32_bf16 v[60:63], v[154:157], v[190:193], v[60:63]
	v_mfma_f32_16x16x32_bf16 v[56:59], v[182:185], v[190:193], v[56:59]
	v_mfma_f32_16x16x32_bf16 v[44:47], v[154:157], v[198:201], v[44:47]
	v_mfma_f32_16x16x32_bf16 v[40:43], v[182:185], v[198:201], v[40:43]
	v_mfma_f32_16x16x32_bf16 v[28:31], v[154:157], v[206:209], v[28:31]
	v_mfma_f32_16x16x32_bf16 v[24:27], v[182:185], v[206:209], v[24:27]
	v_mfma_f32_16x16x32_bf16 v[12:15], v[154:157], v[214:217], v[12:15]
	v_mfma_f32_16x16x32_bf16 v[8:11], v[182:185], v[214:217], v[8:11]
	s_setprio 0
	s_barrier
; #define PG8_STAGE(bufoff, gbase, v0, v1) do { \
;         __builtin_amdgcn_global_load_lds((const unsigned*)((const char*)(gbase) + (v0)), (LAS unsigned*)(lds + (bufoff) + ldsw), 16, 0, 0); \
;         __builtin_amdgcn_global_load_lds((const unsigned*)((const char*)(gbase) + (v1)), (LAS unsigned*)(lds + (bufoff) + ldsw + 8192), 16, 0, 0); } while (0)
; #define PG8_LDA(dst, b, h) do { _Pragma("unroll") for (int m = 0; m < 4; ++m) _Pragma("unroll") for (int k = 0; k < 2; ++k) dst[m][k] = *(const LAS bf16x8*)(lds + PG8_SA(b, h) + aoff + m * 2048 + k * 1024); } while (0)
; #define PG8_LDB(dst, b, h) do { _Pragma("unroll") for (int n = 0; n < 2; ++n) _Pragma("unroll") for (int k = 0; k < 2; ++k) dst[n][k] = *(const LAS bf16x8*)(lds + PG8_SB(b, h) + boff + n * 2048 + k * 1024); } while (0)
; #define PG8_MMA(ai, bj, At, Bt) do { __builtin_amdgcn_s_setprio(1); _Pragma("unroll") for (int m = 0; m < 4; ++m) _Pragma("unroll") for (int n = 0; n < 2; ++n) _Pragma("unroll") for (int k = 0; k < 2; ++k) \
;         acc[ai][bj][m][n] = __builtin_amdgcn_mfma_f32_16x16x32_bf16(Bt[n][k], At[m][k], acc[ai][bj][m][n], 0, 0, 0); __builtin_amdgcn_s_setprio(0); } while (0)
; #define PG8_WAIT_V(n) asm volatile("s_waitcnt vmcnt(" #n ")" ::: "memory")
; #define PG8_WAIT_L(n) asm volatile("s_waitcnt lgkmcnt(" #n ")" ::: "memory")
; #define PG8_BAR __builtin_amdgcn_s_barrier()
; #define PG8_SCHED __builtin_amdgcn_sched_barrier(0)
; template <class Epi, class Sched>
; __device__ __forceinline__ void gemm_phase(LAS unsigned char* lds, const Sched& S, const Epi& E) {
;     ...
;             PG8_STAGE(PG8_SB(0, 1), b2 + xhB, xB0, xB1);
;             PG8_WAIT_V(6); PG8_BAR; PG8_MMA(1, 1, At, B1); PG8_BAR;
;             PG8_LDB(B0, 1, 0); PG8_SCHED; PG8_LDA(At, 1, 0); PG8_STAGE(PG8_SA(0, 1), a2 + xhA, xA0, xA1);
;             PG8_WAIT_L(8); PG8_BAR; PG8_WAIT_L(0); PG8_MMA(0, 0, At, B0); PG8_BAR; PG8_SCHED;
;             PG8_LDB(B1, 1, 1); PG8_STAGE(PG8_SB(1, 0), b3, xB0, xB1);
;             PG8_BAR; PG8_WAIT_L(0); PG8_MMA(0, 1, At, B1); PG8_BAR;
	s_add_u32 s82, s40, 0x80000
	s_addc_u32 s83, s41, 0
	s_add_i32 s23, s71, s49
	v_lshl_add_u64 v[150:151], s[82:83], 0, v[142:143]
	s_mov_b32 m0, s23
	s_nop 0
	global_load_lds_dwordx4 v[150:151], off
	v_lshl_add_u64 v[150:151], s[82:83], 0, v[134:135]
	s_add_i32 m0, s23, 0x2000
	s_nop 0
	global_load_lds_dwordx4 v[150:151], off
	s_waitcnt vmcnt(6)
	s_barrier
	s_setprio 1
	v_mfma_f32_16x16x32_bf16 v[52:55], v[218:221], v[186:189], v[52:55]
	v_mfma_f32_16x16x32_bf16 v[48:51], v[226:229], v[186:189], v[48:51]
	v_mfma_f32_16x16x32_bf16 v[36:39], v[218:221], v[194:197], v[36:39]
	v_mfma_f32_16x16x32_bf16 v[32:35], v[226:229], v[194:197], v[32:35]
	v_mfma_f32_16x16x32_bf16 v[20:23], v[218:221], v[202:205], v[20:23]
	v_mfma_f32_16x16x32_bf16 v[16:19], v[226:229], v[202:205], v[16:19]
	v_mfma_f32_16x16x32_bf16 v[4:7], v[218:221], v[210:213], v[4:7]
	v_mfma_f32_16x16x32_bf16 v[0:3], v[226:229], v[210:213], v[0:3]
	v_mfma_f32_16x16x32_bf16 v[52:55], v[222:225], v[190:193], v[52:55]
	v_mfma_f32_16x16x32_bf16 v[48:51], v[230:233], v[190:193], v[48:51]
	v_mfma_f32_16x16x32_bf16 v[36:39], v[222:225], v[198:201], v[36:39]
	v_mfma_f32_16x16x32_bf16 v[32:35], v[230:233], v[198:201], v[32:35]
	v_mfma_f32_16x16x32_bf16 v[20:23], v[222:225], v[206:209], v[20:23]
	v_mfma_f32_16x16x32_bf16 v[16:19], v[230:233], v[206:209], v[16:19]
	v_mfma_f32_16x16x32_bf16 v[4:7], v[222:225], v[214:217], v[4:7]
	v_mfma_f32_16x16x32_bf16 v[0:3], v[230:233], v[214:217], v[0:3]
	s_setprio 0
	s_barrier
	s_add_i32 s23, 0, 0x18000
	v_add_u32_e32 v149, s23, v147
	ds_read_b128 v[150:153], v149
	ds_read_b128 v[154:157], v149 offset:1024
	ds_read_b128 v[158:161], v149 offset:2048
	ds_read_b128 v[182:185], v149 offset:3072
	s_add_u32 s42, s42, 0x80000
	s_addc_u32 s43, s43, 0
	s_mov_b32 m0, s54
	v_lshl_add_u64 v[218:219], s[42:43], 0, v[142:143]
	ds_read_b128 v[186:189], v148 offset:32768
	ds_read_b128 v[190:193], v148 offset:33792
	ds_read_b128 v[194:197], v148 offset:34816
	ds_read_b128 v[198:201], v148 offset:35840
	ds_read_b128 v[202:205], v148 offset:36864
	ds_read_b128 v[206:209], v148 offset:37888
	ds_read_b128 v[210:213], v148 offset:38912
	ds_read_b128 v[214:217], v148 offset:39936
	global_load_lds_dwordx4 v[218:219], off
	v_lshl_add_u64 v[218:219], s[42:43], 0, v[134:135]
	s_mov_b32 m0, s55
	s_nop 0
	global_load_lds_dwordx4 v[218:219], off
	s_waitcnt lgkmcnt(8)
	s_barrier
	s_waitcnt lgkmcnt(0)
	s_setprio 1
	v_mfma_f32_16x16x32_bf16 v[124:127], v[150:153], v[186:189], v[124:127]
	v_mfma_f32_16x16x32_bf16 v[120:123], v[158:161], v[186:189], v[120:123]
	v_mfma_f32_16x16x32_bf16 v[108:111], v[150:153], v[194:197], v[108:111]
	v_mfma_f32_16x16x32_bf16 v[104:107], v[158:161], v[194:197], v[104:107]
	v_mfma_f32_16x16x32_bf16 v[92:95], v[150:153], v[202:205], v[92:95]
	v_mfma_f32_16x16x32_bf16 v[88:91], v[158:161], v[202:205], v[88:91]
	v_mfma_f32_16x16x32_bf16 v[76:79], v[150:153], v[210:213], v[76:79]
	v_mfma_f32_16x16x32_bf16 v[72:75], v[158:161], v[210:213], v[72:75]
	v_mfma_f32_16x16x32_bf16 v[124:127], v[154:157], v[190:193], v[124:127]
	v_mfma_f32_16x16x32_bf16 v[120:123], v[182:185], v[190:193], v[120:123]
	v_mfma_f32_16x16x32_bf16 v[108:111], v[154:157], v[198:201], v[108:111]
	v_mfma_f32_16x16x32_bf16 v[104:107], v[182:185], v[198:201], v[104:107]
	v_mfma_f32_16x16x32_bf16 v[92:95], v[154:157], v[206:209], v[92:95]
	v_mfma_f32_16x16x32_bf16 v[88:91], v[182:185], v[206:209], v[88:91]
	v_mfma_f32_16x16x32_bf16 v[76:79], v[154:157], v[214:217], v[76:79]
	v_mfma_f32_16x16x32_bf16 v[72:75], v[182:185], v[214:217], v[72:75]
	s_setprio 0
	s_barrier
	s_add_i32 s42, 0, 0x1c000
	s_add_i32 s23, s23, s49
	v_add_u32_e32 v149, s42, v147
	v_lshl_add_u64 v[138:139], v[138:139], 0, s[44:45]
	s_mov_b32 m0, s23
	ds_read_b128 v[218:221], v149
	ds_read_b128 v[222:225], v149 offset:1024
	ds_read_b128 v[226:229], v149 offset:2048
	ds_read_b128 v[230:233], v149 offset:3072
	global_load_lds_dwordx4 v[138:139], off
	v_lshl_add_u64 v[138:139], v[140:141], 0, s[44:45]
	s_add_i32 m0, s23, 0x2000
	s_nop 0
	global_load_lds_dwordx4 v[138:139], off
	s_barrier
; #define PG8_STAGE(bufoff, gbase, v0, v1) do { \
;         __builtin_amdgcn_global_load_lds((const unsigned*)((const char*)(gbase) + (v0)), (LAS unsigned*)(lds + (bufoff) + ldsw), 16, 0, 0); \
;         __builtin_amdgcn_global_load_lds((const unsigned*)((const char*)(gbase) + (v1)), (LAS unsigned*)(lds + (bufoff) + ldsw + 8192), 16, 0, 0); } while (0)
; #define PG8_LDA(dst, b, h) do { _Pragma("unroll") for (int m = 0; m < 4; ++m) _Pragma("unroll") for (int k = 0; k < 2; ++k) dst[m][k] = *(const LAS bf16x8*)(lds + PG8_SA(b, h) + aoff + m * 2048 + k * 1024); } while (0)
; #define PG8_MMA(ai, bj, At, Bt) do { __builtin_amdgcn_s_setprio(1); _Pragma("unroll") for (int m = 0; m < 4; ++m) _Pragma("unroll") for (int n = 0; n < 2; ++n) _Pragma("unroll") for (int k = 0; k < 2; ++k) \
;         acc[ai][bj][m][n] = __builtin_amdgcn_mfma_f32_16x16x32_bf16(Bt[n][k], At[m][k], acc[ai][bj][m][n], 0, 0, 0); __builtin_amdgcn_s_setprio(0); } while (0)
; #define PG8_WAIT_V(n) asm volatile("s_waitcnt vmcnt(" #n ")" ::: "memory")
; #define PG8_WAIT_L(n) asm volatile("s_waitcnt lgkmcnt(" #n ")" ::: "memory")
; #define PG8_BAR __builtin_amdgcn_s_barrier()
; #define PG8_SCHED __builtin_amdgcn_sched_barrier(0)
; template <class Epi, class Sched>
; __device__ __forceinline__ void gemm_phase(LAS unsigned char* lds, const Sched& S, const Epi& E) {
;     ...
;             const bool last = (t == nt - 2);
;             const char* a1 = cA + (size_t)(t + 1) * kstep;
;             const char* a2 = last ? nA : cA + (size_t)(t + 2) * kstep; const char* b2 = last ? nB : cB + (size_t)(t + 2) * kstep;
;             const char* a3 = a2 + kstep; const char* b3 = b2 + kstep;
;             const unsigned xA0 = last ? nvA0 : vA0, xA1 = last ? nvA1 : vA1, xB0 = last ? nvB0 : vB0, xB1 = last ? nvB1 : vB1;
;             const size_t xhA = last ? nhA : hA, xhB = last ? nhB : hB;
;     ...
;             PG8_BAR; PG8_WAIT_L(0); PG8_MMA(0, 1, At, B1); PG8_BAR;
;             PG8_LDA(At, 1, 1); PG8_STAGE(PG8_SA(1, 0), a3, xA0, xA1);
;             PG8_BAR; PG8_WAIT_L(0); PG8_MMA(1, 0, At, B0); PG8_BAR; PG8_SCHED;
;             PG8_STAGE(PG8_SB(1, 1), b3 + xhB, xB0, xB1);
;             PG8_WAIT_V(6); PG8_BAR; PG8_MMA(1, 1, At, B1); PG8_BAR;
;         }
	s_waitcnt lgkmcnt(0)
	s_setprio 1
	v_mfma_f32_16x16x32_bf16 v[116:119], v[218:221], v[186:189], v[116:119]
	v_mfma_f32_16x16x32_bf16 v[112:115], v[226:229], v[186:189], v[112:115]
	v_mfma_f32_16x16x32_bf16 v[100:103], v[218:221], v[194:197], v[100:103]
	v_mfma_f32_16x16x32_bf16 v[96:99], v[226:229], v[194:197], v[96:99]
	v_mfma_f32_16x16x32_bf16 v[84:87], v[218:221], v[202:205], v[84:87]
	v_mfma_f32_16x16x32_bf16 v[80:83], v[226:229], v[202:205], v[80:83]
	v_mfma_f32_16x16x32_bf16 v[68:71], v[218:221], v[210:213], v[68:71]
	v_mfma_f32_16x16x32_bf16 v[64:67], v[226:229], v[210:213], v[64:67]
	v_mfma_f32_16x16x32_bf16 v[116:119], v[222:225], v[190:193], v[116:119]
	v_mfma_f32_16x16x32_bf16 v[112:115], v[230:233], v[190:193], v[112:115]
	v_mfma_f32_16x16x32_bf16 v[100:103], v[222:225], v[198:201], v[100:103]
	v_mfma_f32_16x16x32_bf16 v[96:99], v[230:233], v[198:201], v[96:99]
	v_mfma_f32_16x16x32_bf16 v[84:87], v[222:225], v[206:209], v[84:87]
	v_mfma_f32_16x16x32_bf16 v[80:83], v[230:233], v[206:209], v[80:83]
	v_mfma_f32_16x16x32_bf16 v[68:71], v[222:225], v[214:217], v[68:71]
	v_mfma_f32_16x16x32_bf16 v[64:67], v[230:233], v[214:217], v[64:67]
	s_setprio 0
	s_barrier
	s_mov_b32 m0, s66
	v_lshl_add_u64 v[138:139], v[234:235], 0, s[44:45]
	ds_read_b128 v[186:189], v148 offset:49152
	ds_read_b128 v[190:193], v148 offset:50176
	ds_read_b128 v[194:197], v148 offset:51200
	ds_read_b128 v[198:201], v148 offset:52224
	ds_read_b128 v[202:205], v148 offset:53248
	ds_read_b128 v[206:209], v148 offset:54272
	ds_read_b128 v[210:213], v148 offset:55296
	ds_read_b128 v[214:217], v148 offset:56320
	global_load_lds_dwordx4 v[138:139], off
	v_lshl_add_u64 v[138:139], v[236:237], 0, s[44:45]
	s_mov_b32 m0, s67
	s_nop 0
	global_load_lds_dwordx4 v[138:139], off
	s_barrier
	s_waitcnt lgkmcnt(0)
	s_setprio 1
	v_mfma_f32_16x16x32_bf16 v[60:63], v[150:153], v[186:189], v[60:63]
	v_mfma_f32_16x16x32_bf16 v[56:59], v[158:161], v[186:189], v[56:59]
	v_mfma_f32_16x16x32_bf16 v[44:47], v[150:153], v[194:197], v[44:47]
	v_mfma_f32_16x16x32_bf16 v[40:43], v[158:161], v[194:197], v[40:43]
	v_mfma_f32_16x16x32_bf16 v[28:31], v[150:153], v[202:205], v[28:31]
	v_mfma_f32_16x16x32_bf16 v[24:27], v[158:161], v[202:205], v[24:27]
	v_mfma_f32_16x16x32_bf16 v[12:15], v[150:153], v[210:213], v[12:15]
	v_mfma_f32_16x16x32_bf16 v[8:11], v[158:161], v[210:213], v[8:11]
	v_mfma_f32_16x16x32_bf16 v[60:63], v[154:157], v[190:193], v[60:63]
	v_mfma_f32_16x16x32_bf16 v[56:59], v[182:185], v[190:193], v[56:59]
	v_mfma_f32_16x16x32_bf16 v[44:47], v[154:157], v[198:201], v[44:47]
	v_mfma_f32_16x16x32_bf16 v[40:43], v[182:185], v[198:201], v[40:43]
	v_mfma_f32_16x16x32_bf16 v[28:31], v[154:157], v[206:209], v[28:31]
	v_mfma_f32_16x16x32_bf16 v[24:27], v[182:185], v[206:209], v[24:27]
	v_mfma_f32_16x16x32_bf16 v[12:15], v[154:157], v[214:217], v[12:15]
	v_mfma_f32_16x16x32_bf16 v[8:11], v[182:185], v[214:217], v[8:11]
	s_setprio 0
	s_barrier
	s_add_u32 s40, s40, 0x80080
	s_addc_u32 s41, s41, 0
	s_add_i32 s23, s42, s49
	v_lshl_add_u64 v[138:139], s[40:41], 0, v[142:143]
	s_mov_b32 m0, s23
	v_lshl_add_u64 v[134:135], s[40:41], 0, v[134:135]
	global_load_lds_dwordx4 v[138:139], off
	s_add_i32 m0, s23, 0x2000
	s_nop 0
	global_load_lds_dwordx4 v[134:135], off
	s_waitcnt vmcnt(6)
	s_barrier
	s_setprio 1
	v_mfma_f32_16x16x32_bf16 v[52:55], v[218:221], v[186:189], v[52:55]
	v_mfma_f32_16x16x32_bf16 v[48:51], v[226:229], v[186:189], v[48:51]
	v_mfma_f32_16x16x32_bf16 v[36:39], v[218:221], v[194:197], v[36:39]
	v_mfma_f32_16x16x32_bf16 v[32:35], v[226:229], v[194:197], v[32:35]
	v_mfma_f32_16x16x32_bf16 v[20:23], v[218:221], v[202:205], v[20:23]
	v_mfma_f32_16x16x32_bf16 v[16:19], v[226:229], v[202:205], v[16:19]
	v_mfma_f32_16x16x32_bf16 v[4:7], v[218:221], v[210:213], v[4:7]
	v_mfma_f32_16x16x32_bf16 v[0:3], v[226:229], v[210:213], v[0:3]
	v_mfma_f32_16x16x32_bf16 v[52:55], v[222:225], v[190:193], v[52:55]
	v_mfma_f32_16x16x32_bf16 v[48:51], v[230:233], v[190:193], v[48:51]
	v_mfma_f32_16x16x32_bf16 v[36:39], v[222:225], v[198:201], v[36:39]
	v_mfma_f32_16x16x32_bf16 v[32:35], v[230:233], v[198:201], v[32:35]
	v_mfma_f32_16x16x32_bf16 v[20:23], v[222:225], v[206:209], v[20:23]
	v_mfma_f32_16x16x32_bf16 v[16:19], v[230:233], v[206:209], v[16:19]
	v_mfma_f32_16x16x32_bf16 v[4:7], v[222:225], v[214:217], v[4:7]
	v_mfma_f32_16x16x32_bf16 v[0:3], v[230:233], v[214:217], v[0:3]
	s_setprio 0
	s_add_i32 s21, s21, 2
	s_add_u32 s34, s34, 0x100
	s_addc_u32 s35, s35, 0
	s_add_u32 s38, s38, 0x100
	s_addc_u32 s39, s39, 0
	s_cmp_gt_u32 s21, 29
	s_cbranch_scc1 .Lrot_exit_2
	s_cmp_eq_u32 s21, 28
	s_cselect_b64 s[42:43], -1, 0
	s_and_b64 vcc, exec, s[42:43]
	v_mov_b64_e32 v[134:135], v[130:131]
	v_mov_b64_e32 v[142:143], v[128:129]
	s_mov_b64 s[40:41], s[26:27]
	s_cbranch_vccnz .Lrot_join_2
	v_mov_b64_e32 v[134:135], v[132:133]
	v_mov_b64_e32 v[142:143], v[136:137]
	s_mov_b64 s[40:41], s[38:39]

; #define PG8_STAGE(bufoff, gbase, v0, v1) do { \
;         __builtin_amdgcn_global_load_lds((const unsigned*)((const char*)(gbase) + (v0)), (LAS unsigned*)(lds + (bufoff) + ldsw), 16, 0, 0); \
;         __builtin_amdgcn_global_load_lds((const unsigned*)((const char*)(gbase) + (v1)), (LAS unsigned*)(lds + (bufoff) + ldsw + 8192), 16, 0, 0); } while (0)
; #define PG8_LDA(dst, b, h) do { _Pragma("unroll") for (int m = 0; m < 4; ++m) _Pragma("unroll") for (int k = 0; k < 2; ++k) dst[m][k] = *(const LAS bf16x8*)(lds + PG8_SA(b, h) + aoff + m * 2048 + k * 1024); } while (0)
; #define PG8_LDB(dst, b, h) do { _Pragma("unroll") for (int n = 0; n < 2; ++n) _Pragma("unroll") for (int k = 0; k < 2; ++k) dst[n][k] = *(const LAS bf16x8*)(lds + PG8_SB(b, h) + boff + n * 2048 + k * 1024); } while (0)
; #define PG8_MMA(ai, bj, At, Bt) do { __builtin_amdgcn_s_setprio(1); _Pragma("unroll") for (int m = 0; m < 4; ++m) _Pragma("unroll") for (int n = 0; n < 2; ++n) _Pragma("unroll") for (int k = 0; k < 2; ++k) \
;         acc[ai][bj][m][n] = __builtin_amdgcn_mfma_f32_16x16x32_bf16(Bt[n][k], At[m][k], acc[ai][bj][m][n], 0, 0, 0); __builtin_amdgcn_s_setprio(0); } while (0)
; template <class Epi, class Sched>
; __device__ __forceinline__ void gemm_phase(LAS unsigned char* lds, const Sched& S, const Epi& E) {
;     ...
;         for (int t = 0; t < nt; t += 2) {
;             const bool last = (t == nt - 2);
;             const char* a1 = cA + (size_t)(t + 1) * kstep;
;             const char* a2 = last ? nA : cA + (size_t)(t + 2) * kstep; const char* b2 = last ? nB : cB + (size_t)(t + 2) * kstep;
;             const char* a3 = a2 + kstep; const char* b3 = b2 + kstep;
;             const unsigned xA0 = last ? nvA0 : vA0, xA1 = last ? nvA1 : vA1, xB0 = last ? nvB0 : vB0, xB1 = last ? nvB1 : vB1;
;             const size_t xhA = last ? nhA : hA, xhB = last ? nhB : hB;
;             PG8_LDB(B0, 0, 0); PG8_SCHED; PG8_LDA(At, 0, 0); PG8_STAGE(PG8_SA(1, 1), a1 + hA, vA0, vA1);
;             PG8_WAIT_L(8); PG8_BAR; PG8_WAIT_L(0); PG8_MMA(0, 0, At, B0); PG8_BAR; PG8_SCHED;
;             PG8_LDB(B1, 0, 1); PG8_STAGE(PG8_SB(0, 0), b2, xB0, xB1);
;             PG8_BAR; PG8_WAIT_L(0); PG8_MMA(0, 1, At, B1); PG8_BAR;
;             PG8_LDA(At, 0, 1); PG8_STAGE(PG8_SA(0, 0), a2, xA0, xA1);
;             PG8_BAR; PG8_WAIT_L(0); PG8_MMA(1, 0, At, B0); PG8_BAR; PG8_SCHED;
.LBB0_808:
	s_add_u32 s21, s26, 0xfff80080
	s_addc_u32 s69, s27, -1
	s_and_b64 s[40:41], exec, s[40:41]
	s_cselect_b32 s41, s23, s69
	s_cselect_b32 s40, s22, s21
	s_add_i32 s21, 0, 0x10000
	v_add_u32_e32 v138, s21, v155
	ds_read_b128 v[158:161], v138
	ds_read_b128 v[182:185], v138 offset:1024
	ds_read_b128 v[186:189], v138 offset:2048
	ds_read_b128 v[190:193], v138 offset:3072
	v_lshl_add_u64 v[138:139], s[26:27], 0, v[132:133]
	s_add_i32 m0, s48, 0xc000
	ds_read_b128 v[194:197], v143
	ds_read_b128 v[198:201], v143 offset:1024
	ds_read_b128 v[202:205], v143 offset:2048
	ds_read_b128 v[206:209], v143 offset:3072
	ds_read_b128 v[210:213], v143 offset:4096
	ds_read_b128 v[214:217], v143 offset:5120
	ds_read_b128 v[218:221], v143 offset:6144
	ds_read_b128 v[222:225], v143 offset:7168
	global_load_lds_dwordx4 v[138:139], off
	v_lshl_add_u64 v[138:139], s[26:27], 0, v[134:135]
	s_add_i32 m0, s48, 0xe000
	s_nop 0
	global_load_lds_dwordx4 v[138:139], off
	s_waitcnt lgkmcnt(8)
	s_barrier
	s_waitcnt lgkmcnt(0)
	s_setprio 1
	v_mfma_f32_16x16x32_bf16 v[124:127], v[158:161], v[194:197], v[124:127]
	v_mfma_f32_16x16x32_bf16 v[120:123], v[186:189], v[194:197], v[120:123]
	v_mfma_f32_16x16x32_bf16 v[112:115], v[158:161], v[202:205], v[112:115]
	v_mfma_f32_16x16x32_bf16 v[104:107], v[186:189], v[202:205], v[104:107]
	v_mfma_f32_16x16x32_bf16 v[96:99], v[158:161], v[210:213], v[96:99]
	v_mfma_f32_16x16x32_bf16 v[88:91], v[186:189], v[210:213], v[88:91]
	v_mfma_f32_16x16x32_bf16 v[80:83], v[158:161], v[218:221], v[80:83]
	v_mfma_f32_16x16x32_bf16 v[72:75], v[186:189], v[218:221], v[72:75]
	v_mfma_f32_16x16x32_bf16 v[124:127], v[182:185], v[198:201], v[124:127]
	v_mfma_f32_16x16x32_bf16 v[120:123], v[190:193], v[198:201], v[120:123]
	v_mfma_f32_16x16x32_bf16 v[112:115], v[182:185], v[206:209], v[112:115]
	v_mfma_f32_16x16x32_bf16 v[104:107], v[190:193], v[206:209], v[104:107]
	v_mfma_f32_16x16x32_bf16 v[96:99], v[182:185], v[214:217], v[96:99]
	v_mfma_f32_16x16x32_bf16 v[88:91], v[190:193], v[214:217], v[88:91]
	v_mfma_f32_16x16x32_bf16 v[80:83], v[182:185], v[222:225], v[80:83]
	v_mfma_f32_16x16x32_bf16 v[72:75], v[190:193], v[222:225], v[72:75]
	s_setprio 0
	s_barrier
	s_add_i32 s69, 0, 0x14000
	s_add_i32 s21, s21, s43
	v_add_u32_e32 v138, s69, v155
	s_mov_b32 m0, s21
	ds_read_b128 v[226:229], v138
	ds_read_b128 v[230:233], v138 offset:1024
	ds_read_b128 v[234:237], v138 offset:2048
	ds_read_b128 v[238:241], v138 offset:3072
	global_load_lds_dwordx4 v136, s[38:39]
	s_add_i32 m0, s21, 0x2000
	v_mov_b32_e32 v147, v137
	global_load_lds_dwordx4 v146, s[38:39]
	v_lshl_add_u64 v[138:139], s[38:39], 0, v[136:137]
	v_lshl_add_u64 v[140:141], s[38:39], 0, v[146:147]
	s_barrier
	s_waitcnt lgkmcnt(0)
	s_setprio 1
	v_mfma_f32_16x16x32_bf16 v[116:119], v[226:229], v[194:197], v[116:119]
	v_mfma_f32_16x16x32_bf16 v[108:111], v[234:237], v[194:197], v[108:111]
	v_mfma_f32_16x16x32_bf16 v[100:103], v[226:229], v[202:205], v[100:103]
	v_mfma_f32_16x16x32_bf16 v[92:95], v[234:237], v[202:205], v[92:95]
	v_mfma_f32_16x16x32_bf16 v[84:87], v[226:229], v[210:213], v[84:87]
	v_mfma_f32_16x16x32_bf16 v[76:79], v[234:237], v[210:213], v[76:79]
	v_mfma_f32_16x16x32_bf16 v[68:71], v[226:229], v[218:221], v[68:71]
	v_mfma_f32_16x16x32_bf16 v[64:67], v[234:237], v[218:221], v[64:67]
	v_mfma_f32_16x16x32_bf16 v[116:119], v[230:233], v[198:201], v[116:119]
	v_mfma_f32_16x16x32_bf16 v[108:111], v[238:241], v[198:201], v[108:111]
	v_mfma_f32_16x16x32_bf16 v[100:103], v[230:233], v[206:209], v[100:103]
	v_mfma_f32_16x16x32_bf16 v[92:95], v[238:241], v[206:209], v[92:95]
	v_mfma_f32_16x16x32_bf16 v[84:87], v[230:233], v[214:217], v[84:87]
	v_mfma_f32_16x16x32_bf16 v[76:79], v[238:241], v[214:217], v[76:79]
	v_mfma_f32_16x16x32_bf16 v[68:71], v[230:233], v[222:225], v[68:71]
	v_mfma_f32_16x16x32_bf16 v[64:67], v[238:241], v[222:225], v[64:67]
	s_setprio 0
	s_barrier
	s_mov_b32 m0, s48
	v_lshl_add_u64 v[242:243], s[40:41], 0, v[150:151]
	ds_read_b128 v[194:197], v143 offset:16384
	ds_read_b128 v[198:201], v143 offset:17408
	ds_read_b128 v[202:205], v143 offset:18432
	ds_read_b128 v[206:209], v143 offset:19456
	ds_read_b128 v[210:213], v143 offset:20480
	ds_read_b128 v[214:217], v143 offset:21504
	ds_read_b128 v[218:221], v143 offset:22528
	ds_read_b128 v[222:225], v143 offset:23552
	global_load_lds_dwordx4 v[242:243], off
	v_lshl_add_u64 v[244:245], s[40:41], 0, v[148:149]
	s_mov_b32 m0, s49
	s_nop 0
	global_load_lds_dwordx4 v[244:245], off
	s_barrier
	s_waitcnt lgkmcnt(0)
	s_setprio 1
	v_mfma_f32_16x16x32_bf16 v[60:63], v[158:161], v[194:197], v[60:63]
	v_mfma_f32_16x16x32_bf16 v[56:59], v[186:189], v[194:197], v[56:59]
	v_mfma_f32_16x16x32_bf16 v[44:47], v[158:161], v[202:205], v[44:47]
	v_mfma_f32_16x16x32_bf16 v[40:43], v[186:189], v[202:205], v[40:43]
	v_mfma_f32_16x16x32_bf16 v[28:31], v[158:161], v[210:213], v[28:31]
	v_mfma_f32_16x16x32_bf16 v[24:27], v[186:189], v[210:213], v[24:27]
	v_mfma_f32_16x16x32_bf16 v[12:15], v[158:161], v[218:221], v[12:15]
	v_mfma_f32_16x16x32_bf16 v[8:11], v[186:189], v[218:221], v[8:11]
	v_mfma_f32_16x16x32_bf16 v[60:63], v[182:185], v[198:201], v[60:63]
	v_mfma_f32_16x16x32_bf16 v[56:59], v[190:193], v[198:201], v[56:59]
	v_mfma_f32_16x16x32_bf16 v[44:47], v[182:185], v[206:209], v[44:47]
	v_mfma_f32_16x16x32_bf16 v[40:43], v[190:193], v[206:209], v[40:43]
	v_mfma_f32_16x16x32_bf16 v[28:31], v[182:185], v[214:217], v[28:31]
	v_mfma_f32_16x16x32_bf16 v[24:27], v[190:193], v[214:217], v[24:27]
	v_mfma_f32_16x16x32_bf16 v[12:15], v[182:185], v[222:225], v[12:15]
	v_mfma_f32_16x16x32_bf16 v[8:11], v[190:193], v[222:225], v[8:11]
	s_setprio 0
	s_barrier
; #define PG8_STAGE(bufoff, gbase, v0, v1) do { \
;         __builtin_amdgcn_global_load_lds((const unsigned*)((const char*)(gbase) + (v0)), (LAS unsigned*)(lds + (bufoff) + ldsw), 16, 0, 0); \
;         __builtin_amdgcn_global_load_lds((const unsigned*)((const char*)(gbase) + (v1)), (LAS unsigned*)(lds + (bufoff) + ldsw + 8192), 16, 0, 0); } while (0)
; #define PG8_LDA(dst, b, h) do { _Pragma("unroll") for (int m = 0; m < 4; ++m) _Pragma("unroll") for (int k = 0; k < 2; ++k) dst[m][k] = *(const LAS bf16x8*)(lds + PG8_SA(b, h) + aoff + m * 2048 + k * 1024); } while (0)
; #define PG8_LDB(dst, b, h) do { _Pragma("unroll") for (int n = 0; n < 2; ++n) _Pragma("unroll") for (int k = 0; k < 2; ++k) dst[n][k] = *(const LAS bf16x8*)(lds + PG8_SB(b, h) + boff + n * 2048 + k * 1024); } while (0)
; #define PG8_MMA(ai, bj, At, Bt) do { __builtin_amdgcn_s_setprio(1); _Pragma("unroll") for (int m = 0; m < 4; ++m) _Pragma("unroll") for (int n = 0; n < 2; ++n) _Pragma("unroll") for (int k = 0; k < 2; ++k) \
;         acc[ai][bj][m][n] = __builtin_amdgcn_mfma_f32_16x16x32_bf16(Bt[n][k], At[m][k], acc[ai][bj][m][n], 0, 0, 0); __builtin_amdgcn_s_setprio(0); } while (0)
; #define PG8_WAIT_V(n) asm volatile("s_waitcnt vmcnt(" #n ")" ::: "memory")
; #define PG8_WAIT_L(n) asm volatile("s_waitcnt lgkmcnt(" #n ")" ::: "memory")
; #define PG8_BAR __builtin_amdgcn_s_barrier()
; #define PG8_SCHED __builtin_amdgcn_sched_barrier(0)
; template <class Epi, class Sched>
; __device__ __forceinline__ void gemm_phase(LAS unsigned char* lds, const Sched& S, const Epi& E) {
;     ...
;             PG8_STAGE(PG8_SB(0, 1), b2 + xhB, xB0, xB1);
;             PG8_WAIT_V(6); PG8_BAR; PG8_MMA(1, 1, At, B1); PG8_BAR;
;             PG8_LDB(B0, 1, 0); PG8_SCHED; PG8_LDA(At, 1, 0); PG8_STAGE(PG8_SA(0, 1), a2 + xhA, xA0, xA1);
;             PG8_WAIT_L(8); PG8_BAR; PG8_WAIT_L(0); PG8_MMA(0, 0, At, B0); PG8_BAR; PG8_SCHED;
;             PG8_LDB(B1, 1, 1); PG8_STAGE(PG8_SB(1, 0), b3, xB0, xB1);
;             PG8_BAR; PG8_WAIT_L(0); PG8_MMA(0, 1, At, B1); PG8_BAR;
	s_add_u32 s70, s38, 0x80000
	s_addc_u32 s71, s39, 0
	s_add_i32 s21, s69, s43
	s_mov_b32 m0, s21
	s_nop 0
	global_load_lds_dwordx4 v136, s[70:71]
	s_add_i32 m0, s21, 0x2000
	s_nop 0
	global_load_lds_dwordx4 v146, s[70:71]
	s_waitcnt vmcnt(6)
	s_barrier
	s_setprio 1
	v_mfma_f32_16x16x32_bf16 v[52:55], v[226:229], v[194:197], v[52:55]
	v_mfma_f32_16x16x32_bf16 v[48:51], v[234:237], v[194:197], v[48:51]
	v_mfma_f32_16x16x32_bf16 v[36:39], v[226:229], v[202:205], v[36:39]
	v_mfma_f32_16x16x32_bf16 v[32:35], v[234:237], v[202:205], v[32:35]
	v_mfma_f32_16x16x32_bf16 v[20:23], v[226:229], v[210:213], v[20:23]
	v_mfma_f32_16x16x32_bf16 v[16:19], v[234:237], v[210:213], v[16:19]
	v_mfma_f32_16x16x32_bf16 v[4:7], v[226:229], v[218:221], v[4:7]
	v_mfma_f32_16x16x32_bf16 v[0:3], v[234:237], v[218:221], v[0:3]
	v_mfma_f32_16x16x32_bf16 v[52:55], v[230:233], v[198:201], v[52:55]
	v_mfma_f32_16x16x32_bf16 v[48:51], v[238:241], v[198:201], v[48:51]
	v_mfma_f32_16x16x32_bf16 v[36:39], v[230:233], v[206:209], v[36:39]
	v_mfma_f32_16x16x32_bf16 v[32:35], v[238:241], v[206:209], v[32:35]
	v_mfma_f32_16x16x32_bf16 v[20:23], v[230:233], v[214:217], v[20:23]
	v_mfma_f32_16x16x32_bf16 v[16:19], v[238:241], v[214:217], v[16:19]
	v_mfma_f32_16x16x32_bf16 v[4:7], v[230:233], v[222:225], v[4:7]
	v_mfma_f32_16x16x32_bf16 v[0:3], v[238:241], v[222:225], v[0:3]
	s_setprio 0
	s_barrier
	s_add_i32 s21, 0, 0x18000
	v_add_u32_e32 v147, s21, v155
	ds_read_b128 v[158:161], v147
	ds_read_b128 v[182:185], v147 offset:1024
	ds_read_b128 v[186:189], v147 offset:2048
	ds_read_b128 v[190:193], v147 offset:3072
	s_add_u32 s40, s40, 0x80000
	s_addc_u32 s41, s41, 0
	s_mov_b32 m0, s50
	v_lshl_add_u64 v[150:151], s[40:41], 0, v[150:151]
	ds_read_b128 v[194:197], v143 offset:32768
	ds_read_b128 v[198:201], v143 offset:33792
	ds_read_b128 v[202:205], v143 offset:34816
	ds_read_b128 v[206:209], v143 offset:35840
	ds_read_b128 v[210:213], v143 offset:36864
	ds_read_b128 v[214:217], v143 offset:37888
	ds_read_b128 v[218:221], v143 offset:38912
	ds_read_b128 v[222:225], v143 offset:39936
	global_load_lds_dwordx4 v[150:151], off
	v_lshl_add_u64 v[148:149], s[40:41], 0, v[148:149]
	s_mov_b32 m0, s51
	s_nop 0
	global_load_lds_dwordx4 v[148:149], off
	s_waitcnt lgkmcnt(8)
	s_barrier
	s_waitcnt lgkmcnt(0)
	s_setprio 1
	v_mfma_f32_16x16x32_bf16 v[124:127], v[158:161], v[194:197], v[124:127]
	v_mfma_f32_16x16x32_bf16 v[120:123], v[186:189], v[194:197], v[120:123]
	v_mfma_f32_16x16x32_bf16 v[112:115], v[158:161], v[202:205], v[112:115]
	v_mfma_f32_16x16x32_bf16 v[104:107], v[186:189], v[202:205], v[104:107]
	v_mfma_f32_16x16x32_bf16 v[96:99], v[158:161], v[210:213], v[96:99]
	v_mfma_f32_16x16x32_bf16 v[88:91], v[186:189], v[210:213], v[88:91]
	v_mfma_f32_16x16x32_bf16 v[80:83], v[158:161], v[218:221], v[80:83]
	v_mfma_f32_16x16x32_bf16 v[72:75], v[186:189], v[218:221], v[72:75]
	v_mfma_f32_16x16x32_bf16 v[124:127], v[182:185], v[198:201], v[124:127]
	v_mfma_f32_16x16x32_bf16 v[120:123], v[190:193], v[198:201], v[120:123]
	v_mfma_f32_16x16x32_bf16 v[112:115], v[182:185], v[206:209], v[112:115]
	v_mfma_f32_16x16x32_bf16 v[104:107], v[190:193], v[206:209], v[104:107]
	v_mfma_f32_16x16x32_bf16 v[96:99], v[182:185], v[214:217], v[96:99]
	v_mfma_f32_16x16x32_bf16 v[88:91], v[190:193], v[214:217], v[88:91]
	v_mfma_f32_16x16x32_bf16 v[80:83], v[182:185], v[222:225], v[80:83]
	v_mfma_f32_16x16x32_bf16 v[72:75], v[190:193], v[222:225], v[72:75]
	s_setprio 0
	s_barrier
	s_add_i32 s40, 0, 0x1c000
	s_add_i32 s21, s21, s43
	v_add_u32_e32 v147, s40, v155
	v_lshl_add_u64 v[138:139], v[138:139], 0, s[44:45]
	s_mov_b32 m0, s21
	ds_read_b128 v[148:151], v147
	ds_read_b128 v[226:229], v147 offset:1024
	ds_read_b128 v[230:233], v147 offset:2048
	ds_read_b128 v[234:237], v147 offset:3072
	global_load_lds_dwordx4 v[138:139], off
	v_lshl_add_u64 v[138:139], v[140:141], 0, s[44:45]
	s_add_i32 m0, s21, 0x2000
	s_nop 0
	global_load_lds_dwordx4 v[138:139], off
	s_barrier
; #define PG8_STAGE(bufoff, gbase, v0, v1) do { \
;         __builtin_amdgcn_global_load_lds((const unsigned*)((const char*)(gbase) + (v0)), (LAS unsigned*)(lds + (bufoff) + ldsw), 16, 0, 0); \
;         __builtin_amdgcn_global_load_lds((const unsigned*)((const char*)(gbase) + (v1)), (LAS unsigned*)(lds + (bufoff) + ldsw + 8192), 16, 0, 0); } while (0)
; #define PG8_LDA(dst, b, h) do { _Pragma("unroll") for (int m = 0; m < 4; ++m) _Pragma("unroll") for (int k = 0; k < 2; ++k) dst[m][k] = *(const LAS bf16x8*)(lds + PG8_SA(b, h) + aoff + m * 2048 + k * 1024); } while (0)
; #define PG8_MMA(ai, bj, At, Bt) do { __builtin_amdgcn_s_setprio(1); _Pragma("unroll") for (int m = 0; m < 4; ++m) _Pragma("unroll") for (int n = 0; n < 2; ++n) _Pragma("unroll") for (int k = 0; k < 2; ++k) \
;         acc[ai][bj][m][n] = __builtin_amdgcn_mfma_f32_16x16x32_bf16(Bt[n][k], At[m][k], acc[ai][bj][m][n], 0, 0, 0); __builtin_amdgcn_s_setprio(0); } while (0)
; #define PG8_WAIT_V(n) asm volatile("s_waitcnt vmcnt(" #n ")" ::: "memory")
; #define PG8_WAIT_L(n) asm volatile("s_waitcnt lgkmcnt(" #n ")" ::: "memory")
; #define PG8_BAR __builtin_amdgcn_s_barrier()
; #define PG8_SCHED __builtin_amdgcn_sched_barrier(0)
; template <class Epi, class Sched>
; __device__ __forceinline__ void gemm_phase(LAS unsigned char* lds, const Sched& S, const Epi& E) {
;     ...
;             const bool last = (t == nt - 2);
;             const char* a1 = cA + (size_t)(t + 1) * kstep;
;             const char* a2 = last ? nA : cA + (size_t)(t + 2) * kstep; const char* b2 = last ? nB : cB + (size_t)(t + 2) * kstep;
;             const char* a3 = a2 + kstep; const char* b3 = b2 + kstep;
;             const unsigned xA0 = last ? nvA0 : vA0, xA1 = last ? nvA1 : vA1, xB0 = last ? nvB0 : vB0, xB1 = last ? nvB1 : vB1;
;             const size_t xhA = last ? nhA : hA, xhB = last ? nhB : hB;
;     ...
;             PG8_BAR; PG8_WAIT_L(0); PG8_MMA(0, 1, At, B1); PG8_BAR;
;             PG8_LDA(At, 1, 1); PG8_STAGE(PG8_SA(1, 0), a3, xA0, xA1);
;             PG8_BAR; PG8_WAIT_L(0); PG8_MMA(1, 0, At, B0); PG8_BAR; PG8_SCHED;
;             PG8_STAGE(PG8_SB(1, 1), b3 + xhB, xB0, xB1);
;             PG8_WAIT_V(6); PG8_BAR; PG8_MMA(1, 1, At, B1); PG8_BAR;
;         }
	s_waitcnt lgkmcnt(0)
	s_setprio 1
	v_mfma_f32_16x16x32_bf16 v[116:119], v[148:151], v[194:197], v[116:119]
	v_mfma_f32_16x16x32_bf16 v[108:111], v[230:233], v[194:197], v[108:111]
	v_mfma_f32_16x16x32_bf16 v[100:103], v[148:151], v[202:205], v[100:103]
	v_mfma_f32_16x16x32_bf16 v[92:95], v[230:233], v[202:205], v[92:95]
	v_mfma_f32_16x16x32_bf16 v[84:87], v[148:151], v[210:213], v[84:87]
	v_mfma_f32_16x16x32_bf16 v[76:79], v[230:233], v[210:213], v[76:79]
	v_mfma_f32_16x16x32_bf16 v[68:71], v[148:151], v[218:221], v[68:71]
	v_mfma_f32_16x16x32_bf16 v[64:67], v[230:233], v[218:221], v[64:67]
	v_mfma_f32_16x16x32_bf16 v[116:119], v[226:229], v[198:201], v[116:119]
	v_mfma_f32_16x16x32_bf16 v[108:111], v[234:237], v[198:201], v[108:111]
	v_mfma_f32_16x16x32_bf16 v[100:103], v[226:229], v[206:209], v[100:103]
	v_mfma_f32_16x16x32_bf16 v[92:95], v[234:237], v[206:209], v[92:95]
	v_mfma_f32_16x16x32_bf16 v[84:87], v[226:229], v[214:217], v[84:87]
	v_mfma_f32_16x16x32_bf16 v[76:79], v[234:237], v[214:217], v[76:79]
	v_mfma_f32_16x16x32_bf16 v[68:71], v[226:229], v[222:225], v[68:71]
	v_mfma_f32_16x16x32_bf16 v[64:67], v[234:237], v[222:225], v[64:67]
	s_setprio 0
	s_barrier
	s_mov_b32 m0, s64
	v_lshl_add_u64 v[138:139], v[242:243], 0, s[44:45]
	ds_read_b128 v[194:197], v143 offset:49152
	ds_read_b128 v[198:201], v143 offset:50176
	ds_read_b128 v[202:205], v143 offset:51200
	ds_read_b128 v[206:209], v143 offset:52224
	ds_read_b128 v[210:213], v143 offset:53248
	ds_read_b128 v[214:217], v143 offset:54272
	ds_read_b128 v[218:221], v143 offset:55296
	ds_read_b128 v[222:225], v143 offset:56320
	global_load_lds_dwordx4 v[138:139], off
	v_lshl_add_u64 v[138:139], v[244:245], 0, s[44:45]
	s_mov_b32 m0, s65
	s_nop 0
	global_load_lds_dwordx4 v[138:139], off
	s_barrier
	s_waitcnt lgkmcnt(0)
	s_setprio 1
	v_mfma_f32_16x16x32_bf16 v[60:63], v[158:161], v[194:197], v[60:63]
	v_mfma_f32_16x16x32_bf16 v[56:59], v[186:189], v[194:197], v[56:59]
	v_mfma_f32_16x16x32_bf16 v[44:47], v[158:161], v[202:205], v[44:47]
	v_mfma_f32_16x16x32_bf16 v[40:43], v[186:189], v[202:205], v[40:43]
	v_mfma_f32_16x16x32_bf16 v[28:31], v[158:161], v[210:213], v[28:31]
	v_mfma_f32_16x16x32_bf16 v[24:27], v[186:189], v[210:213], v[24:27]
	v_mfma_f32_16x16x32_bf16 v[12:15], v[158:161], v[218:221], v[12:15]
	v_mfma_f32_16x16x32_bf16 v[8:11], v[186:189], v[218:221], v[8:11]
	v_mfma_f32_16x16x32_bf16 v[60:63], v[182:185], v[198:201], v[60:63]
	v_mfma_f32_16x16x32_bf16 v[56:59], v[190:193], v[198:201], v[56:59]
	v_mfma_f32_16x16x32_bf16 v[44:47], v[182:185], v[206:209], v[44:47]
	v_mfma_f32_16x16x32_bf16 v[40:43], v[190:193], v[206:209], v[40:43]
	v_mfma_f32_16x16x32_bf16 v[28:31], v[182:185], v[214:217], v[28:31]
	v_mfma_f32_16x16x32_bf16 v[24:27], v[190:193], v[214:217], v[24:27]
	v_mfma_f32_16x16x32_bf16 v[12:15], v[182:185], v[222:225], v[12:15]
	v_mfma_f32_16x16x32_bf16 v[8:11], v[190:193], v[222:225], v[8:11]
	s_setprio 0
	s_barrier
	s_add_u32 s38, s38, 0x80080
	s_addc_u32 s39, s39, 0
	s_add_i32 s21, s40, s43
	s_mov_b32 m0, s21
	s_nop 0
	global_load_lds_dwordx4 v136, s[38:39]
	s_add_i32 m0, s21, 0x2000
	s_nop 0
	global_load_lds_dwordx4 v146, s[38:39]
	s_waitcnt vmcnt(6)
	s_barrier
	s_setprio 1
	v_mfma_f32_16x16x32_bf16 v[52:55], v[148:151], v[194:197], v[52:55]
	v_mfma_f32_16x16x32_bf16 v[48:51], v[230:233], v[194:197], v[48:51]
	v_mfma_f32_16x16x32_bf16 v[36:39], v[148:151], v[202:205], v[36:39]
	v_mfma_f32_16x16x32_bf16 v[32:35], v[230:233], v[202:205], v[32:35]
	v_mfma_f32_16x16x32_bf16 v[20:23], v[148:151], v[210:213], v[20:23]
	v_mfma_f32_16x16x32_bf16 v[16:19], v[230:233], v[210:213], v[16:19]
	v_mfma_f32_16x16x32_bf16 v[4:7], v[148:151], v[218:221], v[4:7]
	v_mfma_f32_16x16x32_bf16 v[0:3], v[230:233], v[218:221], v[0:3]
	v_mfma_f32_16x16x32_bf16 v[52:55], v[226:229], v[198:201], v[52:55]
	v_mfma_f32_16x16x32_bf16 v[48:51], v[234:237], v[198:201], v[48:51]
	v_mfma_f32_16x16x32_bf16 v[36:39], v[226:229], v[206:209], v[36:39]
	v_mfma_f32_16x16x32_bf16 v[32:35], v[234:237], v[206:209], v[32:35]
	v_mfma_f32_16x16x32_bf16 v[20:23], v[226:229], v[214:217], v[20:23]
	v_mfma_f32_16x16x32_bf16 v[16:19], v[234:237], v[214:217], v[16:19]
	v_mfma_f32_16x16x32_bf16 v[4:7], v[226:229], v[222:225], v[4:7]
	v_mfma_f32_16x16x32_bf16 v[0:3], v[234:237], v[222:225], v[0:3]
	s_setprio 0
	s_add_i32 s15, s15, 2
	s_add_u32 s26, s26, 0x100
	s_addc_u32 s27, s27, 0
	s_add_u32 s34, s34, 0x100
	s_addc_u32 s35, s35, 0
	s_cmp_gt_u32 s15, 29
	s_cbranch_scc1 .Lrot_exit_3
	s_cmp_eq_u32 s15, 28
	s_cselect_b64 s[40:41], -1, 0
	s_and_b64 vcc, exec, s[40:41]
	v_mov_b64_e32 v[148:149], v[130:131]
	v_mov_b64_e32 v[150:151], v[128:129]
	v_mov_b32_e32 v146, v156
	v_mov_b32_e32 v136, v145
	s_mov_b64 s[38:39], s[24:25]
	s_cbranch_vccnz .Lrot_join_3
	v_mov_b64_e32 v[148:149], v[134:135]
	v_mov_b64_e32 v[150:151], v[132:133]
	v_mov_b32_e32 v146, v142
	v_mov_b32_e32 v136, v144
	s_mov_b64 s[38:39], s[34:35]

; #define PG8_STAGE(bufoff, gbase, v0, v1) do { \
;         __builtin_amdgcn_global_load_lds((const unsigned*)((const char*)(gbase) + (v0)), (LAS unsigned*)(lds + (bufoff) + ldsw), 16, 0, 0); \
;         __builtin_amdgcn_global_load_lds((const unsigned*)((const char*)(gbase) + (v1)), (LAS unsigned*)(lds + (bufoff) + ldsw + 8192), 16, 0, 0); } while (0)
; #define PG8_LDA(dst, b, h) do { _Pragma("unroll") for (int m = 0; m < 4; ++m) _Pragma("unroll") for (int k = 0; k < 2; ++k) dst[m][k] = *(const LAS bf16x8*)(lds + PG8_SA(b, h) + aoff + m * 2048 + k * 1024); } while (0)
; #define PG8_LDB(dst, b, h) do { _Pragma("unroll") for (int n = 0; n < 2; ++n) _Pragma("unroll") for (int k = 0; k < 2; ++k) dst[n][k] = *(const LAS bf16x8*)(lds + PG8_SB(b, h) + boff + n * 2048 + k * 1024); } while (0)
; #define PG8_MMA(ai, bj, At, Bt) do { __builtin_amdgcn_s_setprio(1); _Pragma("unroll") for (int m = 0; m < 4; ++m) _Pragma("unroll") for (int n = 0; n < 2; ++n) _Pragma("unroll") for (int k = 0; k < 2; ++k) \
;         acc[ai][bj][m][n] = __builtin_amdgcn_mfma_f32_16x16x32_bf16(Bt[n][k], At[m][k], acc[ai][bj][m][n], 0, 0, 0); __builtin_amdgcn_s_setprio(0); } while (0)
; template <class Epi, class Sched>
; __device__ __forceinline__ void gemm_phase(LAS unsigned char* lds, const Sched& S, const Epi& E) {
;     ...
;         for (int t = 0; t < nt; t += 2) {
;             const bool last = (t == nt - 2);
;             const char* a1 = cA + (size_t)(t + 1) * kstep;
;             const char* a2 = last ? nA : cA + (size_t)(t + 2) * kstep; const char* b2 = last ? nB : cB + (size_t)(t + 2) * kstep;
;             const char* a3 = a2 + kstep; const char* b3 = b2 + kstep;
;             const unsigned xA0 = last ? nvA0 : vA0, xA1 = last ? nvA1 : vA1, xB0 = last ? nvB0 : vB0, xB1 = last ? nvB1 : vB1;
;             const size_t xhA = last ? nhA : hA, xhB = last ? nhB : hB;
;             PG8_LDB(B0, 0, 0); PG8_SCHED; PG8_LDA(At, 0, 0); PG8_STAGE(PG8_SA(1, 1), a1 + hA, vA0, vA1);
;             PG8_WAIT_L(8); PG8_BAR; PG8_WAIT_L(0); PG8_MMA(0, 0, At, B0); PG8_BAR; PG8_SCHED;
;             PG8_LDB(B1, 0, 1); PG8_STAGE(PG8_SB(0, 0), b2, xB0, xB1);
;             PG8_BAR; PG8_WAIT_L(0); PG8_MMA(0, 1, At, B1); PG8_BAR;
;             PG8_LDA(At, 0, 1); PG8_STAGE(PG8_SA(0, 0), a2, xA0, xA1);
;             PG8_BAR; PG8_WAIT_L(0); PG8_MMA(1, 0, At, B0); PG8_BAR; PG8_SCHED;
.LBB0_847:
	s_add_u32 s15, s24, 0xffe00080
	s_addc_u32 s70, s25, -1
	s_and_b64 s[38:39], exec, s[38:39]
	s_cselect_b32 s39, s21, s70
	s_cselect_b32 s38, s20, s15
	s_add_i32 s15, 0, 0x10000
	v_add_u32_e32 v138, s15, v147
	ds_read_b128 v[150:153], v138
	ds_read_b128 v[154:157], v138 offset:1024
	ds_read_b128 v[158:161], v138 offset:2048
	ds_read_b128 v[182:185], v138 offset:3072
	v_lshl_add_u64 v[138:139], s[24:25], 0, v[136:137]
	s_add_i32 m0, s49, 0xc000
	ds_read_b128 v[186:189], v148
	ds_read_b128 v[190:193], v148 offset:1024
	ds_read_b128 v[194:197], v148 offset:2048
	ds_read_b128 v[198:201], v148 offset:3072
	ds_read_b128 v[202:205], v148 offset:4096
	ds_read_b128 v[206:209], v148 offset:5120
	ds_read_b128 v[210:213], v148 offset:6144
	ds_read_b128 v[214:217], v148 offset:7168
	global_load_lds_dwordx4 v[138:139], off
	v_lshl_add_u64 v[138:139], s[24:25], 0, v[132:133]
	s_add_i32 m0, s49, 0xe000
	s_nop 0
	global_load_lds_dwordx4 v[138:139], off
	s_waitcnt lgkmcnt(8)
	s_barrier
	s_waitcnt lgkmcnt(0)
	s_setprio 1
	v_mfma_f32_16x16x32_bf16 v[124:127], v[150:153], v[186:189], v[124:127]
	v_mfma_f32_16x16x32_bf16 v[120:123], v[158:161], v[186:189], v[120:123]
	v_mfma_f32_16x16x32_bf16 v[108:111], v[150:153], v[194:197], v[108:111]
	v_mfma_f32_16x16x32_bf16 v[104:107], v[158:161], v[194:197], v[104:107]
	v_mfma_f32_16x16x32_bf16 v[100:103], v[150:153], v[202:205], v[100:103]
	v_mfma_f32_16x16x32_bf16 v[96:99], v[158:161], v[202:205], v[96:99]
	v_mfma_f32_16x16x32_bf16 v[84:87], v[150:153], v[210:213], v[84:87]
	v_mfma_f32_16x16x32_bf16 v[80:83], v[158:161], v[210:213], v[80:83]
	v_mfma_f32_16x16x32_bf16 v[124:127], v[154:157], v[190:193], v[124:127]
	v_mfma_f32_16x16x32_bf16 v[120:123], v[182:185], v[190:193], v[120:123]
	v_mfma_f32_16x16x32_bf16 v[108:111], v[154:157], v[198:201], v[108:111]
	v_mfma_f32_16x16x32_bf16 v[104:107], v[182:185], v[198:201], v[104:107]
	v_mfma_f32_16x16x32_bf16 v[100:103], v[154:157], v[206:209], v[100:103]
	v_mfma_f32_16x16x32_bf16 v[96:99], v[182:185], v[206:209], v[96:99]
	v_mfma_f32_16x16x32_bf16 v[84:87], v[154:157], v[214:217], v[84:87]
	v_mfma_f32_16x16x32_bf16 v[80:83], v[182:185], v[214:217], v[80:83]
	s_setprio 0
	s_barrier
	s_add_i32 s82, 0, 0x14000
	v_add_u32_e32 v138, s82, v147
	s_add_i32 s15, s15, s48
	ds_read_b128 v[218:221], v138
	ds_read_b128 v[222:225], v138 offset:1024
	ds_read_b128 v[226:229], v138 offset:2048
	ds_read_b128 v[230:233], v138 offset:3072
	v_lshl_add_u64 v[138:139], s[34:35], 0, v[142:143]
	s_mov_b32 m0, s15
	v_lshl_add_u64 v[140:141], s[34:35], 0, v[134:135]
	global_load_lds_dwordx4 v[138:139], off
	s_add_i32 m0, s15, 0x2000
	s_nop 0
	global_load_lds_dwordx4 v[140:141], off
	s_barrier
	s_waitcnt lgkmcnt(0)
	s_setprio 1
	v_mfma_f32_16x16x32_bf16 v[116:119], v[218:221], v[186:189], v[116:119]
	v_mfma_f32_16x16x32_bf16 v[112:115], v[226:229], v[186:189], v[112:115]
	v_mfma_f32_16x16x32_bf16 v[92:95], v[218:221], v[194:197], v[92:95]
	v_mfma_f32_16x16x32_bf16 v[88:91], v[226:229], v[194:197], v[88:91]
	v_mfma_f32_16x16x32_bf16 v[76:79], v[218:221], v[202:205], v[76:79]
	v_mfma_f32_16x16x32_bf16 v[72:75], v[226:229], v[202:205], v[72:75]
	v_mfma_f32_16x16x32_bf16 v[68:71], v[218:221], v[210:213], v[68:71]
	v_mfma_f32_16x16x32_bf16 v[64:67], v[226:229], v[210:213], v[64:67]
	v_mfma_f32_16x16x32_bf16 v[116:119], v[222:225], v[190:193], v[116:119]
	v_mfma_f32_16x16x32_bf16 v[112:115], v[230:233], v[190:193], v[112:115]
	v_mfma_f32_16x16x32_bf16 v[92:95], v[222:225], v[198:201], v[92:95]
	v_mfma_f32_16x16x32_bf16 v[88:91], v[230:233], v[198:201], v[88:91]
	v_mfma_f32_16x16x32_bf16 v[76:79], v[222:225], v[206:209], v[76:79]
	v_mfma_f32_16x16x32_bf16 v[72:75], v[230:233], v[206:209], v[72:75]
	v_mfma_f32_16x16x32_bf16 v[68:71], v[222:225], v[214:217], v[68:71]
	v_mfma_f32_16x16x32_bf16 v[64:67], v[230:233], v[214:217], v[64:67]
	s_setprio 0
	s_barrier
	s_mov_b32 m0, s49
	v_lshl_add_u64 v[234:235], s[38:39], 0, v[142:143]
	ds_read_b128 v[186:189], v148 offset:16384
	ds_read_b128 v[190:193], v148 offset:17408
	ds_read_b128 v[194:197], v148 offset:18432
	ds_read_b128 v[198:201], v148 offset:19456
	ds_read_b128 v[202:205], v148 offset:20480
	ds_read_b128 v[206:209], v148 offset:21504
	ds_read_b128 v[210:213], v148 offset:22528
	ds_read_b128 v[214:217], v148 offset:23552
	global_load_lds_dwordx4 v[234:235], off
	v_lshl_add_u64 v[236:237], s[38:39], 0, v[134:135]
	s_mov_b32 m0, s50
	s_nop 0
	global_load_lds_dwordx4 v[236:237], off
	s_barrier
	s_waitcnt lgkmcnt(0)
	s_setprio 1
	v_mfma_f32_16x16x32_bf16 v[60:63], v[150:153], v[186:189], v[60:63]
	v_mfma_f32_16x16x32_bf16 v[56:59], v[158:161], v[186:189], v[56:59]
	v_mfma_f32_16x16x32_bf16 v[44:47], v[150:153], v[194:197], v[44:47]
	v_mfma_f32_16x16x32_bf16 v[40:43], v[158:161], v[194:197], v[40:43]
	v_mfma_f32_16x16x32_bf16 v[28:31], v[150:153], v[202:205], v[28:31]
	v_mfma_f32_16x16x32_bf16 v[24:27], v[158:161], v[202:205], v[24:27]
	v_mfma_f32_16x16x32_bf16 v[12:15], v[150:153], v[210:213], v[12:15]
	v_mfma_f32_16x16x32_bf16 v[8:11], v[158:161], v[210:213], v[8:11]
	v_mfma_f32_16x16x32_bf16 v[60:63], v[154:157], v[190:193], v[60:63]
	v_mfma_f32_16x16x32_bf16 v[56:59], v[182:185], v[190:193], v[56:59]
	v_mfma_f32_16x16x32_bf16 v[44:47], v[154:157], v[198:201], v[44:47]
	v_mfma_f32_16x16x32_bf16 v[40:43], v[182:185], v[198:201], v[40:43]
	v_mfma_f32_16x16x32_bf16 v[28:31], v[154:157], v[206:209], v[28:31]
	v_mfma_f32_16x16x32_bf16 v[24:27], v[182:185], v[206:209], v[24:27]
	v_mfma_f32_16x16x32_bf16 v[12:15], v[154:157], v[214:217], v[12:15]
	v_mfma_f32_16x16x32_bf16 v[8:11], v[182:185], v[214:217], v[8:11]
	s_setprio 0
	s_barrier
; #define PG8_STAGE(bufoff, gbase, v0, v1) do { \
;         __builtin_amdgcn_global_load_lds((const unsigned*)((const char*)(gbase) + (v0)), (LAS unsigned*)(lds + (bufoff) + ldsw), 16, 0, 0); \
;         __builtin_amdgcn_global_load_lds((const unsigned*)((const char*)(gbase) + (v1)), (LAS unsigned*)(lds + (bufoff) + ldsw + 8192), 16, 0, 0); } while (0)
; #define PG8_LDA(dst, b, h) do { _Pragma("unroll") for (int m = 0; m < 4; ++m) _Pragma("unroll") for (int k = 0; k < 2; ++k) dst[m][k] = *(const LAS bf16x8*)(lds + PG8_SA(b, h) + aoff + m * 2048 + k * 1024); } while (0)
; #define PG8_LDB(dst, b, h) do { _Pragma("unroll") for (int n = 0; n < 2; ++n) _Pragma("unroll") for (int k = 0; k < 2; ++k) dst[n][k] = *(const LAS bf16x8*)(lds + PG8_SB(b, h) + boff + n * 2048 + k * 1024); } while (0)
; #define PG8_MMA(ai, bj, At, Bt) do { __builtin_amdgcn_s_setprio(1); _Pragma("unroll") for (int m = 0; m < 4; ++m) _Pragma("unroll") for (int n = 0; n < 2; ++n) _Pragma("unroll") for (int k = 0; k < 2; ++k) \
;         acc[ai][bj][m][n] = __builtin_amdgcn_mfma_f32_16x16x32_bf16(Bt[n][k], At[m][k], acc[ai][bj][m][n], 0, 0, 0); __builtin_amdgcn_s_setprio(0); } while (0)
; #define PG8_WAIT_V(n) asm volatile("s_waitcnt vmcnt(" #n ")" ::: "memory")
; #define PG8_WAIT_L(n) asm volatile("s_waitcnt lgkmcnt(" #n ")" ::: "memory")
; #define PG8_BAR __builtin_amdgcn_s_barrier()
; #define PG8_SCHED __builtin_amdgcn_sched_barrier(0)
; template <class Epi, class Sched>
; __device__ __forceinline__ void gemm_phase(LAS unsigned char* lds, const Sched& S, const Epi& E) {
;     ...
;             PG8_STAGE(PG8_SB(0, 1), b2 + xhB, xB0, xB1);
;             PG8_WAIT_V(6); PG8_BAR; PG8_MMA(1, 1, At, B1); PG8_BAR;
;             PG8_LDB(B0, 1, 0); PG8_SCHED; PG8_LDA(At, 1, 0); PG8_STAGE(PG8_SA(0, 1), a2 + xhA, xA0, xA1);
;             PG8_WAIT_L(8); PG8_BAR; PG8_WAIT_L(0); PG8_MMA(0, 0, At, B0); PG8_BAR; PG8_SCHED;
;             PG8_LDB(B1, 1, 1); PG8_STAGE(PG8_SB(1, 0), b3, xB0, xB1);
;             PG8_BAR; PG8_WAIT_L(0); PG8_MMA(0, 1, At, B1); PG8_BAR;
	s_add_u32 s70, s34, 0x200000
	s_addc_u32 s71, s35, 0
	s_add_i32 s15, s82, s48
	v_lshl_add_u64 v[150:151], s[70:71], 0, v[142:143]
	s_mov_b32 m0, s15
	s_nop 0
	global_load_lds_dwordx4 v[150:151], off
	v_lshl_add_u64 v[150:151], s[70:71], 0, v[134:135]
	s_add_i32 m0, s15, 0x2000
	s_nop 0
	global_load_lds_dwordx4 v[150:151], off
	s_waitcnt vmcnt(6)
	s_barrier
	s_setprio 1
	v_mfma_f32_16x16x32_bf16 v[52:55], v[218:221], v[186:189], v[52:55]
	v_mfma_f32_16x16x32_bf16 v[48:51], v[226:229], v[186:189], v[48:51]
	v_mfma_f32_16x16x32_bf16 v[36:39], v[218:221], v[194:197], v[36:39]
	v_mfma_f32_16x16x32_bf16 v[32:35], v[226:229], v[194:197], v[32:35]
	v_mfma_f32_16x16x32_bf16 v[20:23], v[218:221], v[202:205], v[20:23]
	v_mfma_f32_16x16x32_bf16 v[16:19], v[226:229], v[202:205], v[16:19]
	v_mfma_f32_16x16x32_bf16 v[4:7], v[218:221], v[210:213], v[4:7]
	v_mfma_f32_16x16x32_bf16 v[0:3], v[226:229], v[210:213], v[0:3]
	v_mfma_f32_16x16x32_bf16 v[52:55], v[222:225], v[190:193], v[52:55]
	v_mfma_f32_16x16x32_bf16 v[48:51], v[230:233], v[190:193], v[48:51]
	v_mfma_f32_16x16x32_bf16 v[36:39], v[222:225], v[198:201], v[36:39]
	v_mfma_f32_16x16x32_bf16 v[32:35], v[230:233], v[198:201], v[32:35]
	v_mfma_f32_16x16x32_bf16 v[20:23], v[222:225], v[206:209], v[20:23]
	v_mfma_f32_16x16x32_bf16 v[16:19], v[230:233], v[206:209], v[16:19]
	v_mfma_f32_16x16x32_bf16 v[4:7], v[222:225], v[214:217], v[4:7]
	v_mfma_f32_16x16x32_bf16 v[0:3], v[230:233], v[214:217], v[0:3]
	s_setprio 0
	s_barrier
	s_add_i32 s15, 0, 0x18000
	v_add_u32_e32 v149, s15, v147
	ds_read_b128 v[150:153], v149
	ds_read_b128 v[154:157], v149 offset:1024
	ds_read_b128 v[158:161], v149 offset:2048
	ds_read_b128 v[182:185], v149 offset:3072
	s_add_u32 s38, s38, 0x200000
	s_addc_u32 s39, s39, 0
	s_mov_b32 m0, s51
	v_lshl_add_u64 v[218:219], s[38:39], 0, v[142:143]
	ds_read_b128 v[186:189], v148 offset:32768
	ds_read_b128 v[190:193], v148 offset:33792
	ds_read_b128 v[194:197], v148 offset:34816
	ds_read_b128 v[198:201], v148 offset:35840
	ds_read_b128 v[202:205], v148 offset:36864
	ds_read_b128 v[206:209], v148 offset:37888
	ds_read_b128 v[210:213], v148 offset:38912
	ds_read_b128 v[214:217], v148 offset:39936
	global_load_lds_dwordx4 v[218:219], off
	v_lshl_add_u64 v[218:219], s[38:39], 0, v[134:135]
	s_mov_b32 m0, s54
	s_nop 0
	global_load_lds_dwordx4 v[218:219], off
	s_waitcnt lgkmcnt(8)
	s_barrier
	s_waitcnt lgkmcnt(0)
	s_setprio 1
	v_mfma_f32_16x16x32_bf16 v[124:127], v[150:153], v[186:189], v[124:127]
	v_mfma_f32_16x16x32_bf16 v[120:123], v[158:161], v[186:189], v[120:123]
	v_mfma_f32_16x16x32_bf16 v[108:111], v[150:153], v[194:197], v[108:111]
	v_mfma_f32_16x16x32_bf16 v[104:107], v[158:161], v[194:197], v[104:107]
	v_mfma_f32_16x16x32_bf16 v[100:103], v[150:153], v[202:205], v[100:103]
	v_mfma_f32_16x16x32_bf16 v[96:99], v[158:161], v[202:205], v[96:99]
	v_mfma_f32_16x16x32_bf16 v[84:87], v[150:153], v[210:213], v[84:87]
	v_mfma_f32_16x16x32_bf16 v[80:83], v[158:161], v[210:213], v[80:83]
	v_mfma_f32_16x16x32_bf16 v[124:127], v[154:157], v[190:193], v[124:127]
	v_mfma_f32_16x16x32_bf16 v[120:123], v[182:185], v[190:193], v[120:123]
	v_mfma_f32_16x16x32_bf16 v[108:111], v[154:157], v[198:201], v[108:111]
	v_mfma_f32_16x16x32_bf16 v[104:107], v[182:185], v[198:201], v[104:107]
	v_mfma_f32_16x16x32_bf16 v[100:103], v[154:157], v[206:209], v[100:103]
	v_mfma_f32_16x16x32_bf16 v[96:99], v[182:185], v[206:209], v[96:99]
	v_mfma_f32_16x16x32_bf16 v[84:87], v[154:157], v[214:217], v[84:87]
	v_mfma_f32_16x16x32_bf16 v[80:83], v[182:185], v[214:217], v[80:83]
	s_setprio 0
	s_barrier
	s_add_i32 s38, 0, 0x1c000
	s_add_i32 s15, s15, s48
	v_add_u32_e32 v149, s38, v147
	v_lshl_add_u64 v[138:139], v[138:139], 0, s[44:45]
	s_mov_b32 m0, s15
	ds_read_b128 v[218:221], v149
	ds_read_b128 v[222:225], v149 offset:1024
	ds_read_b128 v[226:229], v149 offset:2048
	ds_read_b128 v[230:233], v149 offset:3072
	global_load_lds_dwordx4 v[138:139], off
	v_lshl_add_u64 v[138:139], v[140:141], 0, s[44:45]
	s_add_i32 m0, s15, 0x2000
	s_nop 0
	global_load_lds_dwordx4 v[138:139], off
	s_barrier
; #define PG8_STAGE(bufoff, gbase, v0, v1) do { \
;         __builtin_amdgcn_global_load_lds((const unsigned*)((const char*)(gbase) + (v0)), (LAS unsigned*)(lds + (bufoff) + ldsw), 16, 0, 0); \
;         __builtin_amdgcn_global_load_lds((const unsigned*)((const char*)(gbase) + (v1)), (LAS unsigned*)(lds + (bufoff) + ldsw + 8192), 16, 0, 0); } while (0)
; #define PG8_LDA(dst, b, h) do { _Pragma("unroll") for (int m = 0; m < 4; ++m) _Pragma("unroll") for (int k = 0; k < 2; ++k) dst[m][k] = *(const LAS bf16x8*)(lds + PG8_SA(b, h) + aoff + m * 2048 + k * 1024); } while (0)
; #define PG8_MMA(ai, bj, At, Bt) do { __builtin_amdgcn_s_setprio(1); _Pragma("unroll") for (int m = 0; m < 4; ++m) _Pragma("unroll") for (int n = 0; n < 2; ++n) _Pragma("unroll") for (int k = 0; k < 2; ++k) \
;         acc[ai][bj][m][n] = __builtin_amdgcn_mfma_f32_16x16x32_bf16(Bt[n][k], At[m][k], acc[ai][bj][m][n], 0, 0, 0); __builtin_amdgcn_s_setprio(0); } while (0)
; #define PG8_WAIT_V(n) asm volatile("s_waitcnt vmcnt(" #n ")" ::: "memory")
; #define PG8_WAIT_L(n) asm volatile("s_waitcnt lgkmcnt(" #n ")" ::: "memory")
; #define PG8_BAR __builtin_amdgcn_s_barrier()
; #define PG8_SCHED __builtin_amdgcn_sched_barrier(0)
; template <class Epi, class Sched>
; __device__ __forceinline__ void gemm_phase(LAS unsigned char* lds, const Sched& S, const Epi& E) {
;     ...
;             const bool last = (t == nt - 2);
;             const char* a1 = cA + (size_t)(t + 1) * kstep;
;             const char* a2 = last ? nA : cA + (size_t)(t + 2) * kstep; const char* b2 = last ? nB : cB + (size_t)(t + 2) * kstep;
;             const char* a3 = a2 + kstep; const char* b3 = b2 + kstep;
;             const unsigned xA0 = last ? nvA0 : vA0, xA1 = last ? nvA1 : vA1, xB0 = last ? nvB0 : vB0, xB1 = last ? nvB1 : vB1;
;             const size_t xhA = last ? nhA : hA, xhB = last ? nhB : hB;
;     ...
;             PG8_BAR; PG8_WAIT_L(0); PG8_MMA(0, 1, At, B1); PG8_BAR;
;             PG8_LDA(At, 1, 1); PG8_STAGE(PG8_SA(1, 0), a3, xA0, xA1);
;             PG8_BAR; PG8_WAIT_L(0); PG8_MMA(1, 0, At, B0); PG8_BAR; PG8_SCHED;
;             PG8_STAGE(PG8_SB(1, 1), b3 + xhB, xB0, xB1);
;             PG8_WAIT_V(6); PG8_BAR; PG8_MMA(1, 1, At, B1); PG8_BAR;
;         }
	s_waitcnt lgkmcnt(0)
	s_setprio 1
	v_mfma_f32_16x16x32_bf16 v[116:119], v[218:221], v[186:189], v[116:119]
	v_mfma_f32_16x16x32_bf16 v[112:115], v[226:229], v[186:189], v[112:115]
	v_mfma_f32_16x16x32_bf16 v[92:95], v[218:221], v[194:197], v[92:95]
	v_mfma_f32_16x16x32_bf16 v[88:91], v[226:229], v[194:197], v[88:91]
	v_mfma_f32_16x16x32_bf16 v[76:79], v[218:221], v[202:205], v[76:79]
	v_mfma_f32_16x16x32_bf16 v[72:75], v[226:229], v[202:205], v[72:75]
	v_mfma_f32_16x16x32_bf16 v[68:71], v[218:221], v[210:213], v[68:71]
	v_mfma_f32_16x16x32_bf16 v[64:67], v[226:229], v[210:213], v[64:67]
	v_mfma_f32_16x16x32_bf16 v[116:119], v[222:225], v[190:193], v[116:119]
	v_mfma_f32_16x16x32_bf16 v[112:115], v[230:233], v[190:193], v[112:115]
	v_mfma_f32_16x16x32_bf16 v[92:95], v[222:225], v[198:201], v[92:95]
	v_mfma_f32_16x16x32_bf16 v[88:91], v[230:233], v[198:201], v[88:91]
	v_mfma_f32_16x16x32_bf16 v[76:79], v[222:225], v[206:209], v[76:79]
	v_mfma_f32_16x16x32_bf16 v[72:75], v[230:233], v[206:209], v[72:75]
	v_mfma_f32_16x16x32_bf16 v[68:71], v[222:225], v[214:217], v[68:71]
	v_mfma_f32_16x16x32_bf16 v[64:67], v[230:233], v[214:217], v[64:67]
	s_setprio 0
	s_barrier
	s_mov_b32 m0, s65
	v_lshl_add_u64 v[138:139], v[234:235], 0, s[44:45]
	ds_read_b128 v[186:189], v148 offset:49152
	ds_read_b128 v[190:193], v148 offset:50176
	ds_read_b128 v[194:197], v148 offset:51200
	ds_read_b128 v[198:201], v148 offset:52224
	ds_read_b128 v[202:205], v148 offset:53248
	ds_read_b128 v[206:209], v148 offset:54272
	ds_read_b128 v[210:213], v148 offset:55296
	ds_read_b128 v[214:217], v148 offset:56320
	global_load_lds_dwordx4 v[138:139], off
	v_lshl_add_u64 v[138:139], v[236:237], 0, s[44:45]
	s_mov_b32 m0, s66
	s_nop 0
	global_load_lds_dwordx4 v[138:139], off
	s_barrier
	s_waitcnt lgkmcnt(0)
	s_setprio 1
	v_mfma_f32_16x16x32_bf16 v[60:63], v[150:153], v[186:189], v[60:63]
	v_mfma_f32_16x16x32_bf16 v[56:59], v[158:161], v[186:189], v[56:59]
	v_mfma_f32_16x16x32_bf16 v[44:47], v[150:153], v[194:197], v[44:47]
	v_mfma_f32_16x16x32_bf16 v[40:43], v[158:161], v[194:197], v[40:43]
	v_mfma_f32_16x16x32_bf16 v[28:31], v[150:153], v[202:205], v[28:31]
	v_mfma_f32_16x16x32_bf16 v[24:27], v[158:161], v[202:205], v[24:27]
	v_mfma_f32_16x16x32_bf16 v[12:15], v[150:153], v[210:213], v[12:15]
	v_mfma_f32_16x16x32_bf16 v[8:11], v[158:161], v[210:213], v[8:11]
	v_mfma_f32_16x16x32_bf16 v[60:63], v[154:157], v[190:193], v[60:63]
	v_mfma_f32_16x16x32_bf16 v[56:59], v[182:185], v[190:193], v[56:59]
	v_mfma_f32_16x16x32_bf16 v[44:47], v[154:157], v[198:201], v[44:47]
	v_mfma_f32_16x16x32_bf16 v[40:43], v[182:185], v[198:201], v[40:43]
	v_mfma_f32_16x16x32_bf16 v[28:31], v[154:157], v[206:209], v[28:31]
	v_mfma_f32_16x16x32_bf16 v[24:27], v[182:185], v[206:209], v[24:27]
	v_mfma_f32_16x16x32_bf16 v[12:15], v[154:157], v[214:217], v[12:15]
	v_mfma_f32_16x16x32_bf16 v[8:11], v[182:185], v[214:217], v[8:11]
	s_setprio 0
	s_barrier
	s_add_u32 s34, s34, 0x200080
	s_addc_u32 s35, s35, 0
	s_add_i32 s15, s38, s48
	v_lshl_add_u64 v[138:139], s[34:35], 0, v[142:143]
	s_mov_b32 m0, s15
	v_lshl_add_u64 v[134:135], s[34:35], 0, v[134:135]
	global_load_lds_dwordx4 v[138:139], off
	s_add_i32 m0, s15, 0x2000
	s_nop 0
	global_load_lds_dwordx4 v[134:135], off
	s_waitcnt vmcnt(6)
	s_barrier
	s_setprio 1
	v_mfma_f32_16x16x32_bf16 v[52:55], v[218:221], v[186:189], v[52:55]
	v_mfma_f32_16x16x32_bf16 v[48:51], v[226:229], v[186:189], v[48:51]
	v_mfma_f32_16x16x32_bf16 v[36:39], v[218:221], v[194:197], v[36:39]
	v_mfma_f32_16x16x32_bf16 v[32:35], v[226:229], v[194:197], v[32:35]
	v_mfma_f32_16x16x32_bf16 v[20:23], v[218:221], v[202:205], v[20:23]
	v_mfma_f32_16x16x32_bf16 v[16:19], v[226:229], v[202:205], v[16:19]
	v_mfma_f32_16x16x32_bf16 v[4:7], v[218:221], v[210:213], v[4:7]
	v_mfma_f32_16x16x32_bf16 v[0:3], v[226:229], v[210:213], v[0:3]
	v_mfma_f32_16x16x32_bf16 v[52:55], v[222:225], v[190:193], v[52:55]
	v_mfma_f32_16x16x32_bf16 v[48:51], v[230:233], v[190:193], v[48:51]
	v_mfma_f32_16x16x32_bf16 v[36:39], v[222:225], v[198:201], v[36:39]
	v_mfma_f32_16x16x32_bf16 v[32:35], v[230:233], v[198:201], v[32:35]
	v_mfma_f32_16x16x32_bf16 v[20:23], v[222:225], v[206:209], v[20:23]
	v_mfma_f32_16x16x32_bf16 v[16:19], v[230:233], v[206:209], v[16:19]
	v_mfma_f32_16x16x32_bf16 v[4:7], v[222:225], v[214:217], v[4:7]
	v_mfma_f32_16x16x32_bf16 v[0:3], v[230:233], v[214:217], v[0:3]
	s_setprio 0
	s_add_i32 s11, s11, 2
	s_add_u32 s24, s24, 0x100
	s_addc_u32 s25, s25, 0
	s_add_u32 s26, s26, 0x100
	s_addc_u32 s27, s27, 0
	s_cmpk_gt_u32 s11, 0x7d
	s_cbranch_scc1 .Lrot_exit_4
	s_cmpk_eq_i32 s11, 0x7c
	s_cselect_b64 s[38:39], -1, 0
	s_and_b64 vcc, exec, s[38:39]
	v_mov_b64_e32 v[134:135], v[130:131]
	v_mov_b64_e32 v[142:143], v[128:129]
	s_mov_b64 s[34:35], s[22:23]
	s_cbranch_vccnz .Lrot_join_4
	v_mov_b64_e32 v[134:135], v[132:133]
	v_mov_b64_e32 v[142:143], v[136:137]
	s_mov_b64 s[34:35], s[26:27]
